# GEMM k-loop LDS-DMA partition made contiguous per wave (2 m0 writes per k-tile, immediate offsets) on top of previous best
# baseline (speedup 1.0000x reference)
.LBB0_152:
	s_or_saveexec_b64 s[0:1], s[0:1]
	v_mov_b32_e32 v176, 0
	v_mov_b32_e32 v94, 0
	v_mov_b32_e32 v182, 0
	v_mov_b32_e32 v92, 0
	v_mov_b32_e32 v184, 0
	v_mov_b32_e32 v90, 0
	v_mov_b32_e32 v186, 0
	v_mov_b32_e32 v88, 0
	v_mov_b32_e32 v188, 0
	v_mov_b32_e32 v86, 0
	v_mov_b32_e32 v190, 0
	v_mov_b32_e32 v84, 0
	v_mov_b32_e32 v192, 0
	v_mov_b32_e32 v82, 0
	v_mov_b32_e32 v194, 0
	v_mov_b32_e32 v80, 0
	v_mov_b32_e32 v128, 0
	v_mov_b32_e32 v46, 0
	v_mov_b32_e32 v130, 0
	v_mov_b32_e32 v44, 0
	v_mov_b32_e32 v132, 0
	v_mov_b32_e32 v42, 0
	v_mov_b32_e32 v134, 0
	v_mov_b32_e32 v40, 0
	v_mov_b32_e32 v136, 0
	v_mov_b32_e32 v38, 0
	v_mov_b32_e32 v138, 0
	v_mov_b32_e32 v36, 0
	v_mov_b32_e32 v172, 0
	v_mov_b32_e32 v34, 0
	v_mov_b32_e32 v174, 0
	v_mov_b32_e32 v32, 0
	v_mov_b32_e32 v177, 0
	v_mov_b32_e32 v95, 0
	v_mov_b32_e32 v183, 0
	v_mov_b32_e32 v93, 0
	v_mov_b32_e32 v185, 0
	v_mov_b32_e32 v91, 0
	v_mov_b32_e32 v187, 0
	v_mov_b32_e32 v89, 0
	v_mov_b32_e32 v189, 0
	v_mov_b32_e32 v87, 0
	v_mov_b32_e32 v191, 0
	v_mov_b32_e32 v85, 0
	v_mov_b32_e32 v193, 0
	v_mov_b32_e32 v83, 0
	v_mov_b32_e32 v195, 0
	v_mov_b32_e32 v81, 0
	v_mov_b32_e32 v129, 0
	v_mov_b32_e32 v47, 0
	v_mov_b32_e32 v131, 0
	v_mov_b32_e32 v45, 0
	v_mov_b32_e32 v133, 0
	v_mov_b32_e32 v43, 0
	v_mov_b32_e32 v135, 0
	v_mov_b32_e32 v41, 0
	v_mov_b32_e32 v137, 0
	v_mov_b32_e32 v39, 0
	v_mov_b32_e32 v139, 0
	v_mov_b32_e32 v37, 0
	v_mov_b32_e32 v173, 0
	v_mov_b32_e32 v35, 0
	v_mov_b32_e32 v175, 0
	v_mov_b32_e32 v33, 0
	s_xor_b64 exec, exec, s[0:1]
	s_cbranch_execz .LBB0_156
	v_readfirstlane_b32 s78, v170
	v_readfirstlane_b32 s79, v168
	v_readfirstlane_b32 s76, v204
	v_mbcnt_lo_u32_b32 v136, -1, 0
	v_mbcnt_hi_u32_b32 v136, -1, v136
	s_nop 3
	s_lshl_b32 s78, s78, 14
	s_lshl_b32 s79, s79, 13
	s_add_u32 s72, s90, s78
	s_addc_u32 s73, s91, 0
	s_add_u32 s74, s90, s79
	s_addc_u32 s75, s91, 0
	s_add_u32 s74, s74, 0x1ab88000
	s_addc_u32 s75, s75, 0
	v_and_b32_e32 v137, 31, v136
	v_lshrrev_b32_e32 v138, 5, v136
	v_bfe_u32 v139, v136, 2, 2
	v_xor_b32_e32 v138, v138, v139
	v_lshlrev_b32_e32 v138, 4, v138
	v_lshl_or_b32 v137, v137, 6, v138
	v_lshrrev_b32_e32 v139, 10, v204
	v_lshrrev_b32_e32 v138, 1, v139
	v_lshl_or_b32 v128, v138, 11, v137
	v_and_b32_e32 v138, 1, v139
	v_lshl_or_b32 v130, v138, 12, v137
	v_or_b32_e32 v130, 0x4000, v130
	v_xor_b32_e32 v129, 32, v128
	v_xor_b32_e32 v131, 32, v130
	v_lshrrev_b32_e32 v137, 2, v136
	v_lshrrev_b32_e32 v138, 4, v136
	v_xor_b32_e32 v138, v138, v136
	v_and_b32_e32 v138, 3, v138
	v_lshlrev_b32_e32 v138, 4, v138
	v_lshl_or_b32 v137, v137, 6, v138
	v_or_b32_e32 v132, v137, v204
	v_add_u32_e32 v133, 0x1000, v132
	v_add_u32_e32 v134, 0x2000, v132
	v_add_u32_e32 v135, 0x3000, v132
	s_add_u32 m0, s76, 0x2000
	s_nop 0
	global_load_lds_dwordx4 v134, s[72:73]
	s_add_u32 m0, s76, 0x3000
	s_nop 0
	global_load_lds_dwordx4 v135, s[72:73]
	s_add_u32 m0, s76, 0x4000
	s_nop 0
	global_load_lds_dwordx4 v132, s[74:75]
	s_add_u32 m0, s76, 0x5000
	s_nop 0
	global_load_lds_dwordx4 v133, s[74:75]
	s_add_u32 s72, s72, 0x202000
	s_addc_u32 s73, s73, 0
	s_add_u32 s74, s74, 0x2c000
	s_addc_u32 s75, s75, 0
	s_lshl_b32 s78, s76, 2
	s_lshl_b32 s79, s76, 1
	v_sub_u32_e32 v134, v132, v204
	v_lshl_add_u32 v135, v204, 1, v134
	v_lshl_add_u32 v134, v204, 2, v134
	s_add_u32 m0, s78, 0x6000
	s_nop 0
	global_load_lds_dwordx4 v134, s[72:73]
	global_load_lds_dwordx4 v134, s[72:73] offset:1024
	global_load_lds_dwordx4 v134, s[72:73] offset:2048
	global_load_lds_dwordx4 v134, s[72:73] offset:3072
	s_add_u32 m0, s79, 0xa000
	s_nop 0
	global_load_lds_dwordx4 v135, s[74:75]
	global_load_lds_dwordx4 v135, s[74:75] offset:1024
	s_add_u32 s72, s72, 0x202000
	s_addc_u32 s73, s73, 0
	s_add_u32 s74, s74, 0x2c000
	s_addc_u32 s75, s75, 0
	s_add_u32 m0, s78, 0xc000
	s_nop 0
	global_load_lds_dwordx4 v134, s[72:73]
	global_load_lds_dwordx4 v134, s[72:73] offset:1024
	global_load_lds_dwordx4 v134, s[72:73] offset:2048
	global_load_lds_dwordx4 v134, s[72:73] offset:3072
	s_add_u32 m0, s79, 0x10000
	s_nop 0
	global_load_lds_dwordx4 v135, s[74:75]
	global_load_lds_dwordx4 v135, s[74:75] offset:1024
	s_add_u32 s72, s72, 0x202000
	s_addc_u32 s73, s73, 0
	s_add_u32 s74, s74, 0x2c000
	s_addc_u32 s75, s75, 0
	s_waitcnt vmcnt(12)
	s_barrier
	ds_read_b128 v[172:175], v130
	ds_read_b128 v[176:179], v130 offset:2048
	ds_read_b128 v[180:183], v128
	ds_read_b128 v[184:187], v128 offset:4096
	ds_read_b128 v[188:191], v128 offset:8192
	ds_read_b128 v[192:195], v128 offset:12288
	s_waitcnt lgkmcnt(0)
	ds_read_b128 v[220:223], v131
	ds_read_b128 v[224:227], v131 offset:2048
	v_mfma_f32_32x32x16_bf16 v[64:79], v[172:175], v[180:183], 0
	ds_read_b128 v[228:231], v129
	ds_read_b128 v[232:235], v129 offset:4096
	v_mfma_f32_32x32x16_bf16 v[48:63], v[176:179], v[180:183], 0
	ds_read_b128 v[236:239], v129 offset:8192
	ds_read_b128 v[240:243], v129 offset:12288
	v_mfma_f32_32x32x16_bf16 v[16:31], v[172:175], v[184:187], 0
	v_mfma_f32_32x32x16_bf16 v[0:15], v[176:179], v[184:187], 0
	v_mfma_f32_32x32x16_bf16 v[80:95], v[172:175], v[188:191], 0
	v_mfma_f32_32x32x16_bf16 v[112:127], v[176:179], v[188:191], 0
	v_mfma_f32_32x32x16_bf16 v[32:47], v[172:175], v[192:195], 0
	v_mfma_f32_32x32x16_bf16 v[96:111], v[176:179], v[192:195], 0
	s_waitcnt lgkmcnt(0)
	s_waitcnt vmcnt(6)
	s_barrier
	ds_read_b128 v[172:175], v130 offset:24576
	ds_read_b128 v[176:179], v130 offset:26624
	v_mfma_f32_32x32x16_bf16 v[64:79], v[220:223], v[228:231], v[64:79]
	ds_read_b128 v[180:183], v128 offset:24576
	ds_read_b128 v[184:187], v128 offset:28672
	v_mfma_f32_32x32x16_bf16 v[48:63], v[224:227], v[228:231], v[48:63]
	ds_read_b128 v[188:191], v128 offset:32768
	ds_read_b128 v[192:195], v128 offset:36864
	v_mfma_f32_32x32x16_bf16 v[16:31], v[220:223], v[232:235], v[16:31]
	s_add_u32 m0, s78, 0x0
	v_mfma_f32_32x32x16_bf16 v[0:15], v[224:227], v[232:235], v[0:15]
	global_load_lds_dwordx4 v134, s[72:73]
	global_load_lds_dwordx4 v134, s[72:73] offset:1024
	v_mfma_f32_32x32x16_bf16 v[80:95], v[220:223], v[236:239], v[80:95]
	global_load_lds_dwordx4 v134, s[72:73] offset:2048
	global_load_lds_dwordx4 v134, s[72:73] offset:3072
	s_add_u32 m0, s79, 0x4000
	v_mfma_f32_32x32x16_bf16 v[112:127], v[224:227], v[236:239], v[112:127]
	global_load_lds_dwordx4 v135, s[74:75]
	global_load_lds_dwordx4 v135, s[74:75] offset:1024
	v_mfma_f32_32x32x16_bf16 v[32:47], v[220:223], v[240:243], v[32:47]
	s_add_u32 s72, s72, 0x202000
	s_addc_u32 s73, s73, 0
	v_mfma_f32_32x32x16_bf16 v[96:111], v[224:227], v[240:243], v[96:111]
	s_add_u32 s74, s74, 0x2c000
	s_addc_u32 s75, s75, 0
	s_waitcnt lgkmcnt(0)
	ds_read_b128 v[220:223], v131 offset:24576
	ds_read_b128 v[224:227], v131 offset:26624
	v_mfma_f32_32x32x16_bf16 v[64:79], v[172:175], v[180:183], v[64:79]
	ds_read_b128 v[228:231], v129 offset:24576
	ds_read_b128 v[232:235], v129 offset:28672
	v_mfma_f32_32x32x16_bf16 v[48:63], v[176:179], v[180:183], v[48:63]
	ds_read_b128 v[236:239], v129 offset:32768
	ds_read_b128 v[240:243], v129 offset:36864
	v_mfma_f32_32x32x16_bf16 v[16:31], v[172:175], v[184:187], v[16:31]
	v_mfma_f32_32x32x16_bf16 v[0:15], v[176:179], v[184:187], v[0:15]
	v_mfma_f32_32x32x16_bf16 v[80:95], v[172:175], v[188:191], v[80:95]
	v_mfma_f32_32x32x16_bf16 v[112:127], v[176:179], v[188:191], v[112:127]
	v_mfma_f32_32x32x16_bf16 v[32:47], v[172:175], v[192:195], v[32:47]
	v_mfma_f32_32x32x16_bf16 v[96:111], v[176:179], v[192:195], v[96:111]
	s_waitcnt lgkmcnt(0)
	s_waitcnt vmcnt(6)
	s_barrier
	ds_read_b128 v[172:175], v130 offset:49152
	ds_read_b128 v[176:179], v130 offset:51200
	v_mfma_f32_32x32x16_bf16 v[64:79], v[220:223], v[228:231], v[64:79]
	ds_read_b128 v[180:183], v128 offset:49152
	ds_read_b128 v[184:187], v128 offset:53248
	v_mfma_f32_32x32x16_bf16 v[48:63], v[224:227], v[228:231], v[48:63]
	ds_read_b128 v[188:191], v128 offset:57344
	ds_read_b128 v[192:195], v128 offset:61440
	v_mfma_f32_32x32x16_bf16 v[16:31], v[220:223], v[232:235], v[16:31]
	s_add_u32 m0, s78, 0x6000
	v_mfma_f32_32x32x16_bf16 v[0:15], v[224:227], v[232:235], v[0:15]
	global_load_lds_dwordx4 v134, s[72:73]
	global_load_lds_dwordx4 v134, s[72:73] offset:1024
	v_mfma_f32_32x32x16_bf16 v[80:95], v[220:223], v[236:239], v[80:95]
	global_load_lds_dwordx4 v134, s[72:73] offset:2048
	global_load_lds_dwordx4 v134, s[72:73] offset:3072
	s_add_u32 m0, s79, 0xa000
	v_mfma_f32_32x32x16_bf16 v[112:127], v[224:227], v[236:239], v[112:127]
	global_load_lds_dwordx4 v135, s[74:75]
	global_load_lds_dwordx4 v135, s[74:75] offset:1024
	v_mfma_f32_32x32x16_bf16 v[32:47], v[220:223], v[240:243], v[32:47]
	s_add_u32 s72, s72, 0x202000
	s_addc_u32 s73, s73, 0
	v_mfma_f32_32x32x16_bf16 v[96:111], v[224:227], v[240:243], v[96:111]
	s_add_u32 s74, s74, 0x2c000
	s_addc_u32 s75, s75, 0
	s_waitcnt lgkmcnt(0)
	ds_read_b128 v[220:223], v131 offset:49152
	ds_read_b128 v[224:227], v131 offset:51200
	v_mfma_f32_32x32x16_bf16 v[64:79], v[172:175], v[180:183], v[64:79]
	ds_read_b128 v[228:231], v129 offset:49152
	ds_read_b128 v[232:235], v129 offset:53248
	v_mfma_f32_32x32x16_bf16 v[48:63], v[176:179], v[180:183], v[48:63]
	ds_read_b128 v[236:239], v129 offset:57344
	ds_read_b128 v[240:243], v129 offset:61440
	v_mfma_f32_32x32x16_bf16 v[16:31], v[172:175], v[184:187], v[16:31]
	v_mfma_f32_32x32x16_bf16 v[0:15], v[176:179], v[184:187], v[0:15]
	v_mfma_f32_32x32x16_bf16 v[80:95], v[172:175], v[188:191], v[80:95]
	v_mfma_f32_32x32x16_bf16 v[112:127], v[176:179], v[188:191], v[112:127]
	v_mfma_f32_32x32x16_bf16 v[32:47], v[172:175], v[192:195], v[32:47]
	v_mfma_f32_32x32x16_bf16 v[96:111], v[176:179], v[192:195], v[96:111]
	s_waitcnt lgkmcnt(0)
	s_waitcnt vmcnt(6)
	s_barrier
	ds_read_b128 v[172:175], v130
	ds_read_b128 v[176:179], v130 offset:2048
	v_mfma_f32_32x32x16_bf16 v[64:79], v[220:223], v[228:231], v[64:79]
	ds_read_b128 v[180:183], v128
	ds_read_b128 v[184:187], v128 offset:4096
	v_mfma_f32_32x32x16_bf16 v[48:63], v[224:227], v[228:231], v[48:63]
	ds_read_b128 v[188:191], v128 offset:8192
	ds_read_b128 v[192:195], v128 offset:12288
	v_mfma_f32_32x32x16_bf16 v[16:31], v[220:223], v[232:235], v[16:31]
	s_add_u32 m0, s78, 0xc000
	v_mfma_f32_32x32x16_bf16 v[0:15], v[224:227], v[232:235], v[0:15]
	global_load_lds_dwordx4 v134, s[72:73]
	global_load_lds_dwordx4 v134, s[72:73] offset:1024
	v_mfma_f32_32x32x16_bf16 v[80:95], v[220:223], v[236:239], v[80:95]
	global_load_lds_dwordx4 v134, s[72:73] offset:2048
	global_load_lds_dwordx4 v134, s[72:73] offset:3072
	s_add_u32 m0, s79, 0x10000
	v_mfma_f32_32x32x16_bf16 v[112:127], v[224:227], v[236:239], v[112:127]
	global_load_lds_dwordx4 v135, s[74:75]
	global_load_lds_dwordx4 v135, s[74:75] offset:1024
	v_mfma_f32_32x32x16_bf16 v[32:47], v[220:223], v[240:243], v[32:47]
	s_add_u32 s72, s72, 0x202000
	s_addc_u32 s73, s73, 0
	v_mfma_f32_32x32x16_bf16 v[96:111], v[224:227], v[240:243], v[96:111]
	s_add_u32 s74, s74, 0x2c000
	s_addc_u32 s75, s75, 0
	s_waitcnt lgkmcnt(0)
	s_mov_b32 s77, 8
.Lgemm_p1_loop:
	ds_read_b128 v[220:223], v131
	ds_read_b128 v[224:227], v131 offset:2048
	v_mfma_f32_32x32x16_bf16 v[64:79], v[172:175], v[180:183], v[64:79]
	ds_read_b128 v[228:231], v129
	ds_read_b128 v[232:235], v129 offset:4096
	v_mfma_f32_32x32x16_bf16 v[48:63], v[176:179], v[180:183], v[48:63]
	ds_read_b128 v[236:239], v129 offset:8192
	ds_read_b128 v[240:243], v129 offset:12288
	v_mfma_f32_32x32x16_bf16 v[16:31], v[172:175], v[184:187], v[16:31]
	v_mfma_f32_32x32x16_bf16 v[0:15], v[176:179], v[184:187], v[0:15]
	v_mfma_f32_32x32x16_bf16 v[80:95], v[172:175], v[188:191], v[80:95]
	v_mfma_f32_32x32x16_bf16 v[112:127], v[176:179], v[188:191], v[112:127]
	v_mfma_f32_32x32x16_bf16 v[32:47], v[172:175], v[192:195], v[32:47]
	v_mfma_f32_32x32x16_bf16 v[96:111], v[176:179], v[192:195], v[96:111]
	s_waitcnt lgkmcnt(0)
	s_waitcnt vmcnt(6)
	s_barrier
	ds_read_b128 v[172:175], v130 offset:24576
	ds_read_b128 v[176:179], v130 offset:26624
	v_mfma_f32_32x32x16_bf16 v[64:79], v[220:223], v[228:231], v[64:79]
	ds_read_b128 v[180:183], v128 offset:24576
	ds_read_b128 v[184:187], v128 offset:28672
	v_mfma_f32_32x32x16_bf16 v[48:63], v[224:227], v[228:231], v[48:63]
	ds_read_b128 v[188:191], v128 offset:32768
	ds_read_b128 v[192:195], v128 offset:36864
	v_mfma_f32_32x32x16_bf16 v[16:31], v[220:223], v[232:235], v[16:31]
	s_add_u32 m0, s78, 0x0
	v_mfma_f32_32x32x16_bf16 v[0:15], v[224:227], v[232:235], v[0:15]
	global_load_lds_dwordx4 v134, s[72:73]
	global_load_lds_dwordx4 v134, s[72:73] offset:1024
	v_mfma_f32_32x32x16_bf16 v[80:95], v[220:223], v[236:239], v[80:95]
	global_load_lds_dwordx4 v134, s[72:73] offset:2048
	global_load_lds_dwordx4 v134, s[72:73] offset:3072
	s_add_u32 m0, s79, 0x4000
	v_mfma_f32_32x32x16_bf16 v[112:127], v[224:227], v[236:239], v[112:127]
	global_load_lds_dwordx4 v135, s[74:75]
	global_load_lds_dwordx4 v135, s[74:75] offset:1024
	v_mfma_f32_32x32x16_bf16 v[32:47], v[220:223], v[240:243], v[32:47]
	s_add_u32 s72, s72, 0x202000
	s_addc_u32 s73, s73, 0
	v_mfma_f32_32x32x16_bf16 v[96:111], v[224:227], v[240:243], v[96:111]
	s_add_u32 s74, s74, 0x2c000
	s_addc_u32 s75, s75, 0
	s_waitcnt lgkmcnt(0)
	ds_read_b128 v[220:223], v131 offset:24576
	ds_read_b128 v[224:227], v131 offset:26624
	v_mfma_f32_32x32x16_bf16 v[64:79], v[172:175], v[180:183], v[64:79]
	ds_read_b128 v[228:231], v129 offset:24576
	ds_read_b128 v[232:235], v129 offset:28672
	v_mfma_f32_32x32x16_bf16 v[48:63], v[176:179], v[180:183], v[48:63]
	ds_read_b128 v[236:239], v129 offset:32768
	ds_read_b128 v[240:243], v129 offset:36864
	v_mfma_f32_32x32x16_bf16 v[16:31], v[172:175], v[184:187], v[16:31]
	v_mfma_f32_32x32x16_bf16 v[0:15], v[176:179], v[184:187], v[0:15]
	v_mfma_f32_32x32x16_bf16 v[80:95], v[172:175], v[188:191], v[80:95]
	v_mfma_f32_32x32x16_bf16 v[112:127], v[176:179], v[188:191], v[112:127]
	v_mfma_f32_32x32x16_bf16 v[32:47], v[172:175], v[192:195], v[32:47]
	v_mfma_f32_32x32x16_bf16 v[96:111], v[176:179], v[192:195], v[96:111]
	s_waitcnt lgkmcnt(0)
	s_waitcnt vmcnt(6)
	s_barrier
	ds_read_b128 v[172:175], v130 offset:49152
	ds_read_b128 v[176:179], v130 offset:51200
	v_mfma_f32_32x32x16_bf16 v[64:79], v[220:223], v[228:231], v[64:79]
	ds_read_b128 v[180:183], v128 offset:49152
	ds_read_b128 v[184:187], v128 offset:53248
	v_mfma_f32_32x32x16_bf16 v[48:63], v[224:227], v[228:231], v[48:63]
	ds_read_b128 v[188:191], v128 offset:57344
	ds_read_b128 v[192:195], v128 offset:61440
	v_mfma_f32_32x32x16_bf16 v[16:31], v[220:223], v[232:235], v[16:31]
	s_add_u32 m0, s78, 0x6000
	v_mfma_f32_32x32x16_bf16 v[0:15], v[224:227], v[232:235], v[0:15]
	global_load_lds_dwordx4 v134, s[72:73]
	global_load_lds_dwordx4 v134, s[72:73] offset:1024
	v_mfma_f32_32x32x16_bf16 v[80:95], v[220:223], v[236:239], v[80:95]
	global_load_lds_dwordx4 v134, s[72:73] offset:2048
	global_load_lds_dwordx4 v134, s[72:73] offset:3072
	s_add_u32 m0, s79, 0xa000
	v_mfma_f32_32x32x16_bf16 v[112:127], v[224:227], v[236:239], v[112:127]
	global_load_lds_dwordx4 v135, s[74:75]
	global_load_lds_dwordx4 v135, s[74:75] offset:1024
	v_mfma_f32_32x32x16_bf16 v[32:47], v[220:223], v[240:243], v[32:47]
	s_add_u32 s72, s72, 0x202000
	s_addc_u32 s73, s73, 0
	v_mfma_f32_32x32x16_bf16 v[96:111], v[224:227], v[240:243], v[96:111]
	s_add_u32 s74, s74, 0x2c000
	s_addc_u32 s75, s75, 0
	s_waitcnt lgkmcnt(0)
	ds_read_b128 v[220:223], v131 offset:49152
	ds_read_b128 v[224:227], v131 offset:51200
	v_mfma_f32_32x32x16_bf16 v[64:79], v[172:175], v[180:183], v[64:79]
	ds_read_b128 v[228:231], v129 offset:49152
	ds_read_b128 v[232:235], v129 offset:53248
	v_mfma_f32_32x32x16_bf16 v[48:63], v[176:179], v[180:183], v[48:63]
	ds_read_b128 v[236:239], v129 offset:57344
	ds_read_b128 v[240:243], v129 offset:61440
	v_mfma_f32_32x32x16_bf16 v[16:31], v[172:175], v[184:187], v[16:31]
	v_mfma_f32_32x32x16_bf16 v[0:15], v[176:179], v[184:187], v[0:15]
	v_mfma_f32_32x32x16_bf16 v[80:95], v[172:175], v[188:191], v[80:95]
	v_mfma_f32_32x32x16_bf16 v[112:127], v[176:179], v[188:191], v[112:127]
	v_mfma_f32_32x32x16_bf16 v[32:47], v[172:175], v[192:195], v[32:47]
	v_mfma_f32_32x32x16_bf16 v[96:111], v[176:179], v[192:195], v[96:111]
	s_waitcnt lgkmcnt(0)
	s_waitcnt vmcnt(6)
	s_barrier
	ds_read_b128 v[172:175], v130
	ds_read_b128 v[176:179], v130 offset:2048
	v_mfma_f32_32x32x16_bf16 v[64:79], v[220:223], v[228:231], v[64:79]
	ds_read_b128 v[180:183], v128
	ds_read_b128 v[184:187], v128 offset:4096
	v_mfma_f32_32x32x16_bf16 v[48:63], v[224:227], v[228:231], v[48:63]
	ds_read_b128 v[188:191], v128 offset:8192
	ds_read_b128 v[192:195], v128 offset:12288
	v_mfma_f32_32x32x16_bf16 v[16:31], v[220:223], v[232:235], v[16:31]
	s_add_u32 m0, s78, 0xc000
	v_mfma_f32_32x32x16_bf16 v[0:15], v[224:227], v[232:235], v[0:15]
	global_load_lds_dwordx4 v134, s[72:73]
	global_load_lds_dwordx4 v134, s[72:73] offset:1024
	v_mfma_f32_32x32x16_bf16 v[80:95], v[220:223], v[236:239], v[80:95]
	global_load_lds_dwordx4 v134, s[72:73] offset:2048
	global_load_lds_dwordx4 v134, s[72:73] offset:3072
	s_add_u32 m0, s79, 0x10000
	v_mfma_f32_32x32x16_bf16 v[112:127], v[224:227], v[236:239], v[112:127]
	global_load_lds_dwordx4 v135, s[74:75]
	global_load_lds_dwordx4 v135, s[74:75] offset:1024
	v_mfma_f32_32x32x16_bf16 v[32:47], v[220:223], v[240:243], v[32:47]
	s_add_u32 s72, s72, 0x202000
	s_addc_u32 s73, s73, 0
	v_mfma_f32_32x32x16_bf16 v[96:111], v[224:227], v[240:243], v[96:111]
	s_add_u32 s74, s74, 0x2c000
	s_addc_u32 s75, s75, 0
	s_waitcnt lgkmcnt(0)
	s_sub_i32 s77, s77, 1
	s_cmp_lg_u32 s77, 0
	s_cbranch_scc1 .Lgemm_p1_loop
	ds_read_b128 v[220:223], v131
	ds_read_b128 v[224:227], v131 offset:2048
	v_mfma_f32_32x32x16_bf16 v[64:79], v[172:175], v[180:183], v[64:79]
	ds_read_b128 v[228:231], v129
	ds_read_b128 v[232:235], v129 offset:4096
	v_mfma_f32_32x32x16_bf16 v[48:63], v[176:179], v[180:183], v[48:63]
	ds_read_b128 v[236:239], v129 offset:8192
	ds_read_b128 v[240:243], v129 offset:12288
	v_mfma_f32_32x32x16_bf16 v[16:31], v[172:175], v[184:187], v[16:31]
	v_mfma_f32_32x32x16_bf16 v[0:15], v[176:179], v[184:187], v[0:15]
	v_mfma_f32_32x32x16_bf16 v[80:95], v[172:175], v[188:191], v[80:95]
	v_mfma_f32_32x32x16_bf16 v[112:127], v[176:179], v[188:191], v[112:127]
	v_mfma_f32_32x32x16_bf16 v[32:47], v[172:175], v[192:195], v[32:47]
	v_mfma_f32_32x32x16_bf16 v[96:111], v[176:179], v[192:195], v[96:111]
	s_waitcnt lgkmcnt(0)
	s_waitcnt vmcnt(6)
	s_barrier
	ds_read_b128 v[172:175], v130 offset:24576
	ds_read_b128 v[176:179], v130 offset:26624
	v_mfma_f32_32x32x16_bf16 v[64:79], v[220:223], v[228:231], v[64:79]
	ds_read_b128 v[180:183], v128 offset:24576
	ds_read_b128 v[184:187], v128 offset:28672
	v_mfma_f32_32x32x16_bf16 v[48:63], v[224:227], v[228:231], v[48:63]
	ds_read_b128 v[188:191], v128 offset:32768
	ds_read_b128 v[192:195], v128 offset:36864
	v_mfma_f32_32x32x16_bf16 v[16:31], v[220:223], v[232:235], v[16:31]
	s_add_u32 m0, s78, 0x0
	v_mfma_f32_32x32x16_bf16 v[0:15], v[224:227], v[232:235], v[0:15]
	global_load_lds_dwordx4 v134, s[72:73]
	global_load_lds_dwordx4 v134, s[72:73] offset:1024
	v_mfma_f32_32x32x16_bf16 v[80:95], v[220:223], v[236:239], v[80:95]
	global_load_lds_dwordx4 v134, s[72:73] offset:2048
	global_load_lds_dwordx4 v134, s[72:73] offset:3072
	s_add_u32 m0, s79, 0x4000
	v_mfma_f32_32x32x16_bf16 v[112:127], v[224:227], v[236:239], v[112:127]
	global_load_lds_dwordx4 v135, s[74:75]
	global_load_lds_dwordx4 v135, s[74:75] offset:1024
	v_mfma_f32_32x32x16_bf16 v[32:47], v[220:223], v[240:243], v[32:47]
	s_add_u32 s72, s72, 0x202000
	s_addc_u32 s73, s73, 0
	v_mfma_f32_32x32x16_bf16 v[96:111], v[224:227], v[240:243], v[96:111]
	s_add_u32 s74, s74, 0x2c000
	s_addc_u32 s75, s75, 0
	s_waitcnt lgkmcnt(0)
	ds_read_b128 v[220:223], v131 offset:24576
	ds_read_b128 v[224:227], v131 offset:26624
	v_mfma_f32_32x32x16_bf16 v[64:79], v[172:175], v[180:183], v[64:79]
	ds_read_b128 v[228:231], v129 offset:24576
	ds_read_b128 v[232:235], v129 offset:28672
	v_mfma_f32_32x32x16_bf16 v[48:63], v[176:179], v[180:183], v[48:63]
	ds_read_b128 v[236:239], v129 offset:32768
	ds_read_b128 v[240:243], v129 offset:36864
	v_mfma_f32_32x32x16_bf16 v[16:31], v[172:175], v[184:187], v[16:31]
	v_mfma_f32_32x32x16_bf16 v[0:15], v[176:179], v[184:187], v[0:15]
	v_mfma_f32_32x32x16_bf16 v[80:95], v[172:175], v[188:191], v[80:95]
	v_mfma_f32_32x32x16_bf16 v[112:127], v[176:179], v[188:191], v[112:127]
	v_mfma_f32_32x32x16_bf16 v[32:47], v[172:175], v[192:195], v[32:47]
	v_mfma_f32_32x32x16_bf16 v[96:111], v[176:179], v[192:195], v[96:111]
	s_waitcnt lgkmcnt(0)
	s_waitcnt vmcnt(6)
	s_barrier
	ds_read_b128 v[172:175], v130 offset:49152
	ds_read_b128 v[176:179], v130 offset:51200
	v_mfma_f32_32x32x16_bf16 v[64:79], v[220:223], v[228:231], v[64:79]
	ds_read_b128 v[180:183], v128 offset:49152
	ds_read_b128 v[184:187], v128 offset:53248
	v_mfma_f32_32x32x16_bf16 v[48:63], v[224:227], v[228:231], v[48:63]
	ds_read_b128 v[188:191], v128 offset:57344
	ds_read_b128 v[192:195], v128 offset:61440
	v_mfma_f32_32x32x16_bf16 v[16:31], v[220:223], v[232:235], v[16:31]
	s_add_u32 m0, s78, 0x6000
	v_mfma_f32_32x32x16_bf16 v[0:15], v[224:227], v[232:235], v[0:15]
	global_load_lds_dwordx4 v134, s[72:73]
	global_load_lds_dwordx4 v134, s[72:73] offset:1024
	v_mfma_f32_32x32x16_bf16 v[80:95], v[220:223], v[236:239], v[80:95]
	global_load_lds_dwordx4 v134, s[72:73] offset:2048
	global_load_lds_dwordx4 v134, s[72:73] offset:3072
	s_add_u32 m0, s79, 0xa000
	v_mfma_f32_32x32x16_bf16 v[112:127], v[224:227], v[236:239], v[112:127]
	global_load_lds_dwordx4 v135, s[74:75]
	global_load_lds_dwordx4 v135, s[74:75] offset:1024
	v_mfma_f32_32x32x16_bf16 v[32:47], v[220:223], v[240:243], v[32:47]
	s_add_u32 s72, s72, 0x202000
	s_addc_u32 s73, s73, 0
	v_mfma_f32_32x32x16_bf16 v[96:111], v[224:227], v[240:243], v[96:111]
	s_add_u32 s74, s74, 0x2c000
	s_addc_u32 s75, s75, 0
	s_waitcnt lgkmcnt(0)
	ds_read_b128 v[220:223], v131 offset:49152
	ds_read_b128 v[224:227], v131 offset:51200
	v_mfma_f32_32x32x16_bf16 v[64:79], v[172:175], v[180:183], v[64:79]
	ds_read_b128 v[228:231], v129 offset:49152
	ds_read_b128 v[232:235], v129 offset:53248
	v_mfma_f32_32x32x16_bf16 v[48:63], v[176:179], v[180:183], v[48:63]
	ds_read_b128 v[236:239], v129 offset:57344
	ds_read_b128 v[240:243], v129 offset:61440
	v_mfma_f32_32x32x16_bf16 v[16:31], v[172:175], v[184:187], v[16:31]
	v_mfma_f32_32x32x16_bf16 v[0:15], v[176:179], v[184:187], v[0:15]
	v_mfma_f32_32x32x16_bf16 v[80:95], v[172:175], v[188:191], v[80:95]
	v_mfma_f32_32x32x16_bf16 v[112:127], v[176:179], v[188:191], v[112:127]
	v_mfma_f32_32x32x16_bf16 v[32:47], v[172:175], v[192:195], v[32:47]
	v_mfma_f32_32x32x16_bf16 v[96:111], v[176:179], v[192:195], v[96:111]
	s_waitcnt lgkmcnt(0)
	s_waitcnt vmcnt(6)
	s_barrier
	ds_read_b128 v[172:175], v130
	ds_read_b128 v[176:179], v130 offset:2048
	v_mfma_f32_32x32x16_bf16 v[64:79], v[220:223], v[228:231], v[64:79]
	ds_read_b128 v[180:183], v128
	ds_read_b128 v[184:187], v128 offset:4096
	v_mfma_f32_32x32x16_bf16 v[48:63], v[224:227], v[228:231], v[48:63]
	ds_read_b128 v[188:191], v128 offset:8192
	ds_read_b128 v[192:195], v128 offset:12288
	v_mfma_f32_32x32x16_bf16 v[16:31], v[220:223], v[232:235], v[16:31]
	v_mfma_f32_32x32x16_bf16 v[0:15], v[224:227], v[232:235], v[0:15]
	v_mfma_f32_32x32x16_bf16 v[80:95], v[220:223], v[236:239], v[80:95]
	v_mfma_f32_32x32x16_bf16 v[112:127], v[224:227], v[236:239], v[112:127]
	v_mfma_f32_32x32x16_bf16 v[32:47], v[220:223], v[240:243], v[32:47]
	v_mfma_f32_32x32x16_bf16 v[96:111], v[224:227], v[240:243], v[96:111]
	s_waitcnt lgkmcnt(0)
	ds_read_b128 v[220:223], v131
	ds_read_b128 v[224:227], v131 offset:2048
	v_mfma_f32_32x32x16_bf16 v[64:79], v[172:175], v[180:183], v[64:79]
	ds_read_b128 v[228:231], v129
	ds_read_b128 v[232:235], v129 offset:4096
	v_mfma_f32_32x32x16_bf16 v[48:63], v[176:179], v[180:183], v[48:63]
	ds_read_b128 v[236:239], v129 offset:8192
	ds_read_b128 v[240:243], v129 offset:12288
	v_mfma_f32_32x32x16_bf16 v[16:31], v[172:175], v[184:187], v[16:31]
	v_mfma_f32_32x32x16_bf16 v[0:15], v[176:179], v[184:187], v[0:15]
	v_mfma_f32_32x32x16_bf16 v[80:95], v[172:175], v[188:191], v[80:95]
	v_mfma_f32_32x32x16_bf16 v[112:127], v[176:179], v[188:191], v[112:127]
	v_mfma_f32_32x32x16_bf16 v[32:47], v[172:175], v[192:195], v[32:47]
	v_mfma_f32_32x32x16_bf16 v[96:111], v[176:179], v[192:195], v[96:111]
	s_waitcnt lgkmcnt(0)
	s_waitcnt vmcnt(0)
	s_barrier
	ds_read_b128 v[172:175], v130 offset:24576
	ds_read_b128 v[176:179], v130 offset:26624
	v_mfma_f32_32x32x16_bf16 v[64:79], v[220:223], v[228:231], v[64:79]
	ds_read_b128 v[180:183], v128 offset:24576
	ds_read_b128 v[184:187], v128 offset:28672
	v_mfma_f32_32x32x16_bf16 v[48:63], v[224:227], v[228:231], v[48:63]
	ds_read_b128 v[188:191], v128 offset:32768
	ds_read_b128 v[192:195], v128 offset:36864
	v_mfma_f32_32x32x16_bf16 v[16:31], v[220:223], v[232:235], v[16:31]
	v_mfma_f32_32x32x16_bf16 v[0:15], v[224:227], v[232:235], v[0:15]
	v_mfma_f32_32x32x16_bf16 v[80:95], v[220:223], v[236:239], v[80:95]
	v_mfma_f32_32x32x16_bf16 v[112:127], v[224:227], v[236:239], v[112:127]
	v_mfma_f32_32x32x16_bf16 v[32:47], v[220:223], v[240:243], v[32:47]
	v_mfma_f32_32x32x16_bf16 v[96:111], v[224:227], v[240:243], v[96:111]
	s_waitcnt lgkmcnt(0)
	ds_read_b128 v[220:223], v131 offset:24576
	ds_read_b128 v[224:227], v131 offset:26624
	v_mfma_f32_32x32x16_bf16 v[64:79], v[172:175], v[180:183], v[64:79]
	ds_read_b128 v[228:231], v129 offset:24576
	ds_read_b128 v[232:235], v129 offset:28672
	v_mfma_f32_32x32x16_bf16 v[48:63], v[176:179], v[180:183], v[48:63]
	ds_read_b128 v[236:239], v129 offset:32768
	ds_read_b128 v[240:243], v129 offset:36864
	v_mfma_f32_32x32x16_bf16 v[16:31], v[172:175], v[184:187], v[16:31]
	v_mfma_f32_32x32x16_bf16 v[0:15], v[176:179], v[184:187], v[0:15]
	v_mfma_f32_32x32x16_bf16 v[80:95], v[172:175], v[188:191], v[80:95]
	v_mfma_f32_32x32x16_bf16 v[112:127], v[176:179], v[188:191], v[112:127]
	v_mfma_f32_32x32x16_bf16 v[32:47], v[172:175], v[192:195], v[32:47]
	v_mfma_f32_32x32x16_bf16 v[96:111], v[176:179], v[192:195], v[96:111]
	s_waitcnt lgkmcnt(0)
	v_mfma_f32_32x32x16_bf16 v[64:79], v[220:223], v[228:231], v[64:79]
	v_mfma_f32_32x32x16_bf16 v[48:63], v[224:227], v[228:231], v[48:63]
	v_mfma_f32_32x32x16_bf16 v[16:31], v[220:223], v[232:235], v[16:31]
	v_mfma_f32_32x32x16_bf16 v[0:15], v[224:227], v[232:235], v[0:15]
	v_mfma_f32_32x32x16_bf16 v[80:95], v[220:223], v[236:239], v[80:95]
	v_mfma_f32_32x32x16_bf16 v[112:127], v[224:227], v[236:239], v[112:127]
	v_mfma_f32_32x32x16_bf16 v[32:47], v[220:223], v[240:243], v[32:47]
	v_mfma_f32_32x32x16_bf16 v[96:111], v[224:227], v[240:243], v[96:111]
	s_nop 15
	v_mov_b32_e32 v176, v95
	v_mov_b32_e32 v184, v91
	v_mov_b32_e32 v186, v89
	v_mov_b32_e32 v192, v83
	v_mov_b32_e32 v194, v81
	v_mov_b32_e32 v177, v127
	v_mov_b32_e32 v95, v126
	v_mov_b32_e32 v185, v123
	v_mov_b32_e32 v91, v122
	v_mov_b32_e32 v187, v121
	v_mov_b32_e32 v89, v120
	v_mov_b32_e32 v193, v115
	v_mov_b32_e32 v83, v114
	v_mov_b32_e32 v128, v47
	v_mov_b32_e32 v130, v45
	v_mov_b32_e32 v136, v39
	v_mov_b32_e32 v138, v37
	v_mov_b32_e32 v195, v113
	v_mov_b32_e32 v81, v112
	v_mov_b32_e32 v129, v111
	v_mov_b32_e32 v47, v110
	v_mov_b32_e32 v131, v109
	v_mov_b32_e32 v45, v108
	v_mov_b32_e32 v137, v103
	v_mov_b32_e32 v39, v102
	v_mov_b32_e32 v139, v101
	v_mov_b32_e32 v37, v100
	v_mov_b32_e32 v182, v93
	v_mov_b32_e32 v183, v125
	v_mov_b32_e32 v93, v124
	v_mov_b32_e32 v132, v43
	v_mov_b32_e32 v134, v41
	v_mov_b32_e32 v133, v107
	v_mov_b32_e32 v43, v106
	v_mov_b32_e32 v135, v105
	v_mov_b32_e32 v41, v104
	v_mov_b32_e32 v188, v87
	v_mov_b32_e32 v190, v85
	v_mov_b32_e32 v172, v35
	v_mov_b32_e32 v174, v33
	v_mov_b32_e32 v189, v119
	v_mov_b32_e32 v87, v118
	v_mov_b32_e32 v191, v117
	v_mov_b32_e32 v85, v116
	v_mov_b32_e32 v173, v99
	v_mov_b32_e32 v35, v98
	v_mov_b32_e32 v175, v97
	v_mov_b32_e32 v33, v96

.LBB0_535:
	s_or_saveexec_b64 s[0:1], s[0:1]
	v_mov_b32_e32 v127, 0
	v_mov_b64_e32 v[130:131], s[18:19]
	v_mov_b32_e32 v126, 0
	v_mov_b32_e32 v125, 0
	v_mov_b32_e32 v124, 0
	v_mov_b32_e32 v123, 0
	v_mov_b32_e32 v122, 0
	v_mov_b32_e32 v121, 0
	v_mov_b32_e32 v120, 0
	v_mov_b32_e32 v119, 0
	v_mov_b32_e32 v118, 0
	v_mov_b32_e32 v117, 0
	v_mov_b32_e32 v116, 0
	v_mov_b32_e32 v115, 0
	v_mov_b32_e32 v114, 0
	v_mov_b32_e32 v113, 0
	v_mov_b32_e32 v112, 0
	v_mov_b32_e32 v63, 0
	v_mov_b32_e32 v62, 0
	v_mov_b32_e32 v61, 0
	v_mov_b32_e32 v60, 0
	v_mov_b32_e32 v59, 0
	v_mov_b32_e32 v58, 0
	v_mov_b32_e32 v57, 0
	v_mov_b32_e32 v56, 0
	v_mov_b32_e32 v55, 0
	v_mov_b32_e32 v54, 0
	v_mov_b32_e32 v53, 0
	v_mov_b32_e32 v52, 0
	v_mov_b32_e32 v51, 0
	v_mov_b32_e32 v50, 0
	v_mov_b32_e32 v49, 0
	v_mov_b32_e32 v48, 0
	v_mov_b32_e32 v111, 0
	v_mov_b32_e32 v110, 0
	v_mov_b32_e32 v109, 0
	v_mov_b32_e32 v108, 0
	v_mov_b32_e32 v107, 0
	v_mov_b32_e32 v106, 0
	v_mov_b32_e32 v105, 0
	v_mov_b32_e32 v104, 0
	v_mov_b32_e32 v103, 0
	v_mov_b32_e32 v102, 0
	v_mov_b32_e32 v101, 0
	v_mov_b32_e32 v100, 0
	v_mov_b32_e32 v99, 0
	v_mov_b32_e32 v98, 0
	v_mov_b32_e32 v97, 0
	v_mov_b32_e32 v96, 0
	v_mov_b32_e32 v47, 0
	v_mov_b32_e32 v46, 0
	v_mov_b32_e32 v45, 0
	v_mov_b32_e32 v44, 0
	v_mov_b32_e32 v43, 0
	v_mov_b32_e32 v42, 0
	v_mov_b32_e32 v41, 0
	v_mov_b32_e32 v40, 0
	v_mov_b32_e32 v39, 0
	v_mov_b32_e32 v38, 0
	v_mov_b32_e32 v37, 0
	v_mov_b32_e32 v36, 0
	v_mov_b32_e32 v35, 0
	v_mov_b32_e32 v34, 0
	v_mov_b32_e32 v33, 0
	v_mov_b32_e32 v32, 0
	s_xor_b64 exec, exec, s[0:1]
	s_cbranch_execz .LBB0_539
	v_readfirstlane_b32 s78, v166
	v_readfirstlane_b32 s79, v168
	v_readfirstlane_b32 s76, v186
	v_mbcnt_lo_u32_b32 v244, -1, 0
	v_mbcnt_hi_u32_b32 v244, -1, v244
	s_nop 3
	s_lshl_b32 s78, s78, 14
	s_lshl_b32 s79, s79, 13
	s_add_u32 s72, s90, s78
	s_addc_u32 s73, s91, 0
	s_add_u32 s72, s72, 0xf0f0000
	s_addc_u32 s73, s73, 0
	s_add_u32 s74, s90, s79
	s_addc_u32 s75, s91, 0
	s_add_u32 s74, s74, 0x1b108000
	s_addc_u32 s75, s75, 0
	v_and_b32_e32 v245, 31, v244
	v_lshrrev_b32_e32 v246, 5, v244
	v_bfe_u32 v247, v244, 2, 2
	v_xor_b32_e32 v246, v246, v247
	v_lshlrev_b32_e32 v246, 4, v246
	v_lshl_or_b32 v245, v245, 6, v246
	v_lshrrev_b32_e32 v247, 10, v186
	v_lshrrev_b32_e32 v246, 1, v247
	v_lshl_or_b32 v128, v246, 11, v245
	v_and_b32_e32 v246, 1, v247
	v_lshl_or_b32 v167, v246, 12, v245
	v_or_b32_e32 v167, 0x4000, v167
	v_xor_b32_e32 v129, 32, v128
	v_xor_b32_e32 v169, 32, v167
	v_lshrrev_b32_e32 v245, 2, v244
	v_lshrrev_b32_e32 v246, 4, v244
	v_xor_b32_e32 v246, v246, v244
	v_and_b32_e32 v246, 3, v246
	v_lshlrev_b32_e32 v246, 4, v246
	v_lshl_or_b32 v245, v245, 6, v246
	v_or_b32_e32 v170, v245, v186
	v_add_u32_e32 v171, 0x1000, v170
	v_add_u32_e32 v180, 0x2000, v170
	v_add_u32_e32 v181, 0x3000, v170
	s_add_u32 m0, s76, 0x2000
	s_nop 0
	global_load_lds_dwordx4 v180, s[72:73]
	s_add_u32 m0, s76, 0x3000
	s_nop 0
	global_load_lds_dwordx4 v181, s[72:73]
	s_add_u32 m0, s76, 0x4000
	s_nop 0
	global_load_lds_dwordx4 v170, s[74:75]
	s_add_u32 m0, s76, 0x5000
	s_nop 0
	global_load_lds_dwordx4 v171, s[74:75]
	s_add_u32 s72, s72, 0x202000
	s_addc_u32 s73, s73, 0
	s_add_u32 s74, s74, 0x10000
	s_addc_u32 s75, s75, 0
	s_lshl_b32 s78, s76, 2
	s_lshl_b32 s79, s76, 1
	v_sub_u32_e32 v180, v170, v186
	v_lshl_add_u32 v181, v186, 1, v180
	v_lshl_add_u32 v180, v186, 2, v180
	s_add_u32 m0, s78, 0x6000
	s_nop 0
	global_load_lds_dwordx4 v180, s[72:73]
	global_load_lds_dwordx4 v180, s[72:73] offset:1024
	global_load_lds_dwordx4 v180, s[72:73] offset:2048
	global_load_lds_dwordx4 v180, s[72:73] offset:3072
	s_add_u32 m0, s79, 0xa000
	s_nop 0
	global_load_lds_dwordx4 v181, s[74:75]
	global_load_lds_dwordx4 v181, s[74:75] offset:1024
	s_add_u32 s72, s72, 0x202000
	s_addc_u32 s73, s73, 0
	s_add_u32 s74, s74, 0x10000
	s_addc_u32 s75, s75, 0
	s_add_u32 m0, s78, 0xc000
	s_nop 0
	global_load_lds_dwordx4 v180, s[72:73]
	global_load_lds_dwordx4 v180, s[72:73] offset:1024
	global_load_lds_dwordx4 v180, s[72:73] offset:2048
	global_load_lds_dwordx4 v180, s[72:73] offset:3072
	s_add_u32 m0, s79, 0x10000
	s_nop 0
	global_load_lds_dwordx4 v181, s[74:75]
	global_load_lds_dwordx4 v181, s[74:75] offset:1024
	s_add_u32 s72, s72, 0x202000
	s_addc_u32 s73, s73, 0
	s_add_u32 s74, s74, 0x10000
	s_addc_u32 s75, s75, 0
	s_waitcnt vmcnt(12)
	s_barrier
	ds_read_b128 v[212:215], v167
	ds_read_b128 v[216:219], v167 offset:2048
	ds_read_b128 v[220:223], v128
	ds_read_b128 v[224:227], v128 offset:4096
	ds_read_b128 v[228:231], v128 offset:8192
	ds_read_b128 v[232:235], v128 offset:12288
	s_waitcnt lgkmcnt(0)
	ds_read_b128 v[236:239], v169
	ds_read_b128 v[240:243], v169 offset:2048
	v_mfma_f32_32x32x16_bf16 v[80:95], v[212:215], v[220:223], 0
	ds_read_b128 v[132:135], v129
	ds_read_b128 v[136:139], v129 offset:4096
	v_mfma_f32_32x32x16_bf16 v[64:79], v[216:219], v[220:223], 0
	ds_read_b128 v[172:175], v129 offset:8192
	ds_read_b128 v[176:179], v129 offset:12288
	v_mfma_f32_32x32x16_bf16 v[16:31], v[212:215], v[224:227], 0
	v_mfma_f32_32x32x16_bf16 v[0:15], v[216:219], v[224:227], 0
	v_mfma_f32_32x32x16_bf16 v[112:127], v[212:215], v[228:231], 0
	v_mfma_f32_32x32x16_bf16 v[96:111], v[216:219], v[228:231], 0
	v_mfma_f32_32x32x16_bf16 v[48:63], v[212:215], v[232:235], 0
	v_mfma_f32_32x32x16_bf16 v[32:47], v[216:219], v[232:235], 0
	s_waitcnt lgkmcnt(0)
	s_waitcnt vmcnt(6)
	s_barrier
	ds_read_b128 v[212:215], v167 offset:24576
	ds_read_b128 v[216:219], v167 offset:26624
	v_mfma_f32_32x32x16_bf16 v[80:95], v[236:239], v[132:135], v[80:95]
	ds_read_b128 v[220:223], v128 offset:24576
	ds_read_b128 v[224:227], v128 offset:28672
	v_mfma_f32_32x32x16_bf16 v[64:79], v[240:243], v[132:135], v[64:79]
	ds_read_b128 v[228:231], v128 offset:32768
	ds_read_b128 v[232:235], v128 offset:36864
	v_mfma_f32_32x32x16_bf16 v[16:31], v[236:239], v[136:139], v[16:31]
	s_add_u32 m0, s78, 0x0
	v_mfma_f32_32x32x16_bf16 v[0:15], v[240:243], v[136:139], v[0:15]
	global_load_lds_dwordx4 v180, s[72:73]
	global_load_lds_dwordx4 v180, s[72:73] offset:1024
	v_mfma_f32_32x32x16_bf16 v[112:127], v[236:239], v[172:175], v[112:127]
	global_load_lds_dwordx4 v180, s[72:73] offset:2048
	global_load_lds_dwordx4 v180, s[72:73] offset:3072
	s_add_u32 m0, s79, 0x4000
	v_mfma_f32_32x32x16_bf16 v[96:111], v[240:243], v[172:175], v[96:111]
	global_load_lds_dwordx4 v181, s[74:75]
	global_load_lds_dwordx4 v181, s[74:75] offset:1024
	v_mfma_f32_32x32x16_bf16 v[48:63], v[236:239], v[176:179], v[48:63]
	s_add_u32 s72, s72, 0x202000
	s_addc_u32 s73, s73, 0
	v_mfma_f32_32x32x16_bf16 v[32:47], v[240:243], v[176:179], v[32:47]
	s_add_u32 s74, s74, 0x10000
	s_addc_u32 s75, s75, 0
	s_waitcnt lgkmcnt(0)
	ds_read_b128 v[236:239], v169 offset:24576
	ds_read_b128 v[240:243], v169 offset:26624
	v_mfma_f32_32x32x16_bf16 v[80:95], v[212:215], v[220:223], v[80:95]
	ds_read_b128 v[132:135], v129 offset:24576
	ds_read_b128 v[136:139], v129 offset:28672
	v_mfma_f32_32x32x16_bf16 v[64:79], v[216:219], v[220:223], v[64:79]
	ds_read_b128 v[172:175], v129 offset:32768
	ds_read_b128 v[176:179], v129 offset:36864
	v_mfma_f32_32x32x16_bf16 v[16:31], v[212:215], v[224:227], v[16:31]
	v_mfma_f32_32x32x16_bf16 v[0:15], v[216:219], v[224:227], v[0:15]
	v_mfma_f32_32x32x16_bf16 v[112:127], v[212:215], v[228:231], v[112:127]
	v_mfma_f32_32x32x16_bf16 v[96:111], v[216:219], v[228:231], v[96:111]
	v_mfma_f32_32x32x16_bf16 v[48:63], v[212:215], v[232:235], v[48:63]
	v_mfma_f32_32x32x16_bf16 v[32:47], v[216:219], v[232:235], v[32:47]
	s_waitcnt lgkmcnt(0)
	s_waitcnt vmcnt(6)
	s_barrier
	ds_read_b128 v[212:215], v167 offset:49152
	ds_read_b128 v[216:219], v167 offset:51200
	v_mfma_f32_32x32x16_bf16 v[80:95], v[236:239], v[132:135], v[80:95]
	ds_read_b128 v[220:223], v128 offset:49152
	ds_read_b128 v[224:227], v128 offset:53248
	v_mfma_f32_32x32x16_bf16 v[64:79], v[240:243], v[132:135], v[64:79]
	ds_read_b128 v[228:231], v128 offset:57344
	ds_read_b128 v[232:235], v128 offset:61440
	v_mfma_f32_32x32x16_bf16 v[16:31], v[236:239], v[136:139], v[16:31]
	s_add_u32 m0, s78, 0x6000
	v_mfma_f32_32x32x16_bf16 v[0:15], v[240:243], v[136:139], v[0:15]
	global_load_lds_dwordx4 v180, s[72:73]
	global_load_lds_dwordx4 v180, s[72:73] offset:1024
	v_mfma_f32_32x32x16_bf16 v[112:127], v[236:239], v[172:175], v[112:127]
	global_load_lds_dwordx4 v180, s[72:73] offset:2048
	global_load_lds_dwordx4 v180, s[72:73] offset:3072
	s_add_u32 m0, s79, 0xa000
	v_mfma_f32_32x32x16_bf16 v[96:111], v[240:243], v[172:175], v[96:111]
	global_load_lds_dwordx4 v181, s[74:75]
	global_load_lds_dwordx4 v181, s[74:75] offset:1024
	v_mfma_f32_32x32x16_bf16 v[48:63], v[236:239], v[176:179], v[48:63]
	s_add_u32 s72, s72, 0x202000
	s_addc_u32 s73, s73, 0
	v_mfma_f32_32x32x16_bf16 v[32:47], v[240:243], v[176:179], v[32:47]
	s_add_u32 s74, s74, 0x10000
	s_addc_u32 s75, s75, 0
	s_waitcnt lgkmcnt(0)
	ds_read_b128 v[236:239], v169 offset:49152
	ds_read_b128 v[240:243], v169 offset:51200
	v_mfma_f32_32x32x16_bf16 v[80:95], v[212:215], v[220:223], v[80:95]
	ds_read_b128 v[132:135], v129 offset:49152
	ds_read_b128 v[136:139], v129 offset:53248
	v_mfma_f32_32x32x16_bf16 v[64:79], v[216:219], v[220:223], v[64:79]
	ds_read_b128 v[172:175], v129 offset:57344
	ds_read_b128 v[176:179], v129 offset:61440
	v_mfma_f32_32x32x16_bf16 v[16:31], v[212:215], v[224:227], v[16:31]
	v_mfma_f32_32x32x16_bf16 v[0:15], v[216:219], v[224:227], v[0:15]
	v_mfma_f32_32x32x16_bf16 v[112:127], v[212:215], v[228:231], v[112:127]
	v_mfma_f32_32x32x16_bf16 v[96:111], v[216:219], v[228:231], v[96:111]
	v_mfma_f32_32x32x16_bf16 v[48:63], v[212:215], v[232:235], v[48:63]
	v_mfma_f32_32x32x16_bf16 v[32:47], v[216:219], v[232:235], v[32:47]
	s_waitcnt lgkmcnt(0)
	s_waitcnt vmcnt(6)
	s_barrier
	ds_read_b128 v[212:215], v167
	ds_read_b128 v[216:219], v167 offset:2048
	v_mfma_f32_32x32x16_bf16 v[80:95], v[236:239], v[132:135], v[80:95]
	ds_read_b128 v[220:223], v128
	ds_read_b128 v[224:227], v128 offset:4096
	v_mfma_f32_32x32x16_bf16 v[64:79], v[240:243], v[132:135], v[64:79]
	ds_read_b128 v[228:231], v128 offset:8192
	ds_read_b128 v[232:235], v128 offset:12288
	v_mfma_f32_32x32x16_bf16 v[16:31], v[236:239], v[136:139], v[16:31]
	s_add_u32 m0, s78, 0xc000
	v_mfma_f32_32x32x16_bf16 v[0:15], v[240:243], v[136:139], v[0:15]
	global_load_lds_dwordx4 v180, s[72:73]
	global_load_lds_dwordx4 v180, s[72:73] offset:1024
	v_mfma_f32_32x32x16_bf16 v[112:127], v[236:239], v[172:175], v[112:127]
	global_load_lds_dwordx4 v180, s[72:73] offset:2048
	global_load_lds_dwordx4 v180, s[72:73] offset:3072
	s_add_u32 m0, s79, 0x10000
	v_mfma_f32_32x32x16_bf16 v[96:111], v[240:243], v[172:175], v[96:111]
	global_load_lds_dwordx4 v181, s[74:75]
	global_load_lds_dwordx4 v181, s[74:75] offset:1024
	v_mfma_f32_32x32x16_bf16 v[48:63], v[236:239], v[176:179], v[48:63]
	s_add_u32 s72, s72, 0x202000
	s_addc_u32 s73, s73, 0
	v_mfma_f32_32x32x16_bf16 v[32:47], v[240:243], v[176:179], v[32:47]
	s_add_u32 s74, s74, 0x10000
	s_addc_u32 s75, s75, 0
	s_waitcnt lgkmcnt(0)
	s_mov_b32 s77, 12
.Lgemm_p3_loop:
	ds_read_b128 v[236:239], v169
	ds_read_b128 v[240:243], v169 offset:2048
	v_mfma_f32_32x32x16_bf16 v[80:95], v[212:215], v[220:223], v[80:95]
	ds_read_b128 v[132:135], v129
	ds_read_b128 v[136:139], v129 offset:4096
	v_mfma_f32_32x32x16_bf16 v[64:79], v[216:219], v[220:223], v[64:79]
	ds_read_b128 v[172:175], v129 offset:8192
	ds_read_b128 v[176:179], v129 offset:12288
	v_mfma_f32_32x32x16_bf16 v[16:31], v[212:215], v[224:227], v[16:31]
	v_mfma_f32_32x32x16_bf16 v[0:15], v[216:219], v[224:227], v[0:15]
	v_mfma_f32_32x32x16_bf16 v[112:127], v[212:215], v[228:231], v[112:127]
	v_mfma_f32_32x32x16_bf16 v[96:111], v[216:219], v[228:231], v[96:111]
	v_mfma_f32_32x32x16_bf16 v[48:63], v[212:215], v[232:235], v[48:63]
	v_mfma_f32_32x32x16_bf16 v[32:47], v[216:219], v[232:235], v[32:47]
	s_waitcnt lgkmcnt(0)
	s_waitcnt vmcnt(6)
	s_barrier
	ds_read_b128 v[212:215], v167 offset:24576
	ds_read_b128 v[216:219], v167 offset:26624
	v_mfma_f32_32x32x16_bf16 v[80:95], v[236:239], v[132:135], v[80:95]
	ds_read_b128 v[220:223], v128 offset:24576
	ds_read_b128 v[224:227], v128 offset:28672
	v_mfma_f32_32x32x16_bf16 v[64:79], v[240:243], v[132:135], v[64:79]
	ds_read_b128 v[228:231], v128 offset:32768
	ds_read_b128 v[232:235], v128 offset:36864
	v_mfma_f32_32x32x16_bf16 v[16:31], v[236:239], v[136:139], v[16:31]
	s_add_u32 m0, s78, 0x0
	v_mfma_f32_32x32x16_bf16 v[0:15], v[240:243], v[136:139], v[0:15]
	global_load_lds_dwordx4 v180, s[72:73]
	global_load_lds_dwordx4 v180, s[72:73] offset:1024
	v_mfma_f32_32x32x16_bf16 v[112:127], v[236:239], v[172:175], v[112:127]
	global_load_lds_dwordx4 v180, s[72:73] offset:2048
	global_load_lds_dwordx4 v180, s[72:73] offset:3072
	s_add_u32 m0, s79, 0x4000
	v_mfma_f32_32x32x16_bf16 v[96:111], v[240:243], v[172:175], v[96:111]
	global_load_lds_dwordx4 v181, s[74:75]
	global_load_lds_dwordx4 v181, s[74:75] offset:1024
	v_mfma_f32_32x32x16_bf16 v[48:63], v[236:239], v[176:179], v[48:63]
	s_add_u32 s72, s72, 0x202000
	s_addc_u32 s73, s73, 0
	v_mfma_f32_32x32x16_bf16 v[32:47], v[240:243], v[176:179], v[32:47]
	s_add_u32 s74, s74, 0x10000
	s_addc_u32 s75, s75, 0
	s_waitcnt lgkmcnt(0)
	ds_read_b128 v[236:239], v169 offset:24576
	ds_read_b128 v[240:243], v169 offset:26624
	v_mfma_f32_32x32x16_bf16 v[80:95], v[212:215], v[220:223], v[80:95]
	ds_read_b128 v[132:135], v129 offset:24576
	ds_read_b128 v[136:139], v129 offset:28672
	v_mfma_f32_32x32x16_bf16 v[64:79], v[216:219], v[220:223], v[64:79]
	ds_read_b128 v[172:175], v129 offset:32768
	ds_read_b128 v[176:179], v129 offset:36864
	v_mfma_f32_32x32x16_bf16 v[16:31], v[212:215], v[224:227], v[16:31]
	v_mfma_f32_32x32x16_bf16 v[0:15], v[216:219], v[224:227], v[0:15]
	v_mfma_f32_32x32x16_bf16 v[112:127], v[212:215], v[228:231], v[112:127]
	v_mfma_f32_32x32x16_bf16 v[96:111], v[216:219], v[228:231], v[96:111]
	v_mfma_f32_32x32x16_bf16 v[48:63], v[212:215], v[232:235], v[48:63]
	v_mfma_f32_32x32x16_bf16 v[32:47], v[216:219], v[232:235], v[32:47]
	s_waitcnt lgkmcnt(0)
	s_waitcnt vmcnt(6)
	s_barrier
	ds_read_b128 v[212:215], v167 offset:49152
	ds_read_b128 v[216:219], v167 offset:51200
	v_mfma_f32_32x32x16_bf16 v[80:95], v[236:239], v[132:135], v[80:95]
	ds_read_b128 v[220:223], v128 offset:49152
	ds_read_b128 v[224:227], v128 offset:53248
	v_mfma_f32_32x32x16_bf16 v[64:79], v[240:243], v[132:135], v[64:79]
	ds_read_b128 v[228:231], v128 offset:57344
	ds_read_b128 v[232:235], v128 offset:61440
	v_mfma_f32_32x32x16_bf16 v[16:31], v[236:239], v[136:139], v[16:31]
	s_add_u32 m0, s78, 0x6000
	v_mfma_f32_32x32x16_bf16 v[0:15], v[240:243], v[136:139], v[0:15]
	global_load_lds_dwordx4 v180, s[72:73]
	global_load_lds_dwordx4 v180, s[72:73] offset:1024
	v_mfma_f32_32x32x16_bf16 v[112:127], v[236:239], v[172:175], v[112:127]
	global_load_lds_dwordx4 v180, s[72:73] offset:2048
	global_load_lds_dwordx4 v180, s[72:73] offset:3072
	s_add_u32 m0, s79, 0xa000
	v_mfma_f32_32x32x16_bf16 v[96:111], v[240:243], v[172:175], v[96:111]
	global_load_lds_dwordx4 v181, s[74:75]
	global_load_lds_dwordx4 v181, s[74:75] offset:1024
	v_mfma_f32_32x32x16_bf16 v[48:63], v[236:239], v[176:179], v[48:63]
	s_add_u32 s72, s72, 0x202000
	s_addc_u32 s73, s73, 0
	v_mfma_f32_32x32x16_bf16 v[32:47], v[240:243], v[176:179], v[32:47]
	s_add_u32 s74, s74, 0x10000
	s_addc_u32 s75, s75, 0
	s_waitcnt lgkmcnt(0)
	ds_read_b128 v[236:239], v169 offset:49152
	ds_read_b128 v[240:243], v169 offset:51200
	v_mfma_f32_32x32x16_bf16 v[80:95], v[212:215], v[220:223], v[80:95]
	ds_read_b128 v[132:135], v129 offset:49152
	ds_read_b128 v[136:139], v129 offset:53248
	v_mfma_f32_32x32x16_bf16 v[64:79], v[216:219], v[220:223], v[64:79]
	ds_read_b128 v[172:175], v129 offset:57344
	ds_read_b128 v[176:179], v129 offset:61440
	v_mfma_f32_32x32x16_bf16 v[16:31], v[212:215], v[224:227], v[16:31]
	v_mfma_f32_32x32x16_bf16 v[0:15], v[216:219], v[224:227], v[0:15]
	v_mfma_f32_32x32x16_bf16 v[112:127], v[212:215], v[228:231], v[112:127]
	v_mfma_f32_32x32x16_bf16 v[96:111], v[216:219], v[228:231], v[96:111]
	v_mfma_f32_32x32x16_bf16 v[48:63], v[212:215], v[232:235], v[48:63]
	v_mfma_f32_32x32x16_bf16 v[32:47], v[216:219], v[232:235], v[32:47]
	s_waitcnt lgkmcnt(0)
	s_waitcnt vmcnt(6)
	s_barrier
	ds_read_b128 v[212:215], v167
	ds_read_b128 v[216:219], v167 offset:2048
	v_mfma_f32_32x32x16_bf16 v[80:95], v[236:239], v[132:135], v[80:95]
	ds_read_b128 v[220:223], v128
	ds_read_b128 v[224:227], v128 offset:4096
	v_mfma_f32_32x32x16_bf16 v[64:79], v[240:243], v[132:135], v[64:79]
	ds_read_b128 v[228:231], v128 offset:8192
	ds_read_b128 v[232:235], v128 offset:12288
	v_mfma_f32_32x32x16_bf16 v[16:31], v[236:239], v[136:139], v[16:31]
	s_add_u32 m0, s78, 0xc000
	v_mfma_f32_32x32x16_bf16 v[0:15], v[240:243], v[136:139], v[0:15]
	global_load_lds_dwordx4 v180, s[72:73]
	global_load_lds_dwordx4 v180, s[72:73] offset:1024
	v_mfma_f32_32x32x16_bf16 v[112:127], v[236:239], v[172:175], v[112:127]
	global_load_lds_dwordx4 v180, s[72:73] offset:2048
	global_load_lds_dwordx4 v180, s[72:73] offset:3072
	s_add_u32 m0, s79, 0x10000
	v_mfma_f32_32x32x16_bf16 v[96:111], v[240:243], v[172:175], v[96:111]
	global_load_lds_dwordx4 v181, s[74:75]
	global_load_lds_dwordx4 v181, s[74:75] offset:1024
	v_mfma_f32_32x32x16_bf16 v[48:63], v[236:239], v[176:179], v[48:63]
	s_add_u32 s72, s72, 0x202000
	s_addc_u32 s73, s73, 0
	v_mfma_f32_32x32x16_bf16 v[32:47], v[240:243], v[176:179], v[32:47]
	s_add_u32 s74, s74, 0x10000
	s_addc_u32 s75, s75, 0
	s_waitcnt lgkmcnt(0)
	s_sub_i32 s77, s77, 1
	s_cmp_lg_u32 s77, 0
	s_cbranch_scc1 .Lgemm_p3_loop
	ds_read_b128 v[236:239], v169
	ds_read_b128 v[240:243], v169 offset:2048
	v_mfma_f32_32x32x16_bf16 v[80:95], v[212:215], v[220:223], v[80:95]
	ds_read_b128 v[132:135], v129
	ds_read_b128 v[136:139], v129 offset:4096
	v_mfma_f32_32x32x16_bf16 v[64:79], v[216:219], v[220:223], v[64:79]
	ds_read_b128 v[172:175], v129 offset:8192
	ds_read_b128 v[176:179], v129 offset:12288
	v_mfma_f32_32x32x16_bf16 v[16:31], v[212:215], v[224:227], v[16:31]
	v_mfma_f32_32x32x16_bf16 v[0:15], v[216:219], v[224:227], v[0:15]
	v_mfma_f32_32x32x16_bf16 v[112:127], v[212:215], v[228:231], v[112:127]
	v_mfma_f32_32x32x16_bf16 v[96:111], v[216:219], v[228:231], v[96:111]
	v_mfma_f32_32x32x16_bf16 v[48:63], v[212:215], v[232:235], v[48:63]
	v_mfma_f32_32x32x16_bf16 v[32:47], v[216:219], v[232:235], v[32:47]
	s_waitcnt lgkmcnt(0)
	s_waitcnt vmcnt(6)
	s_barrier
	ds_read_b128 v[212:215], v167 offset:24576
	ds_read_b128 v[216:219], v167 offset:26624
	v_mfma_f32_32x32x16_bf16 v[80:95], v[236:239], v[132:135], v[80:95]
	ds_read_b128 v[220:223], v128 offset:24576
	ds_read_b128 v[224:227], v128 offset:28672
	v_mfma_f32_32x32x16_bf16 v[64:79], v[240:243], v[132:135], v[64:79]
	ds_read_b128 v[228:231], v128 offset:32768
	ds_read_b128 v[232:235], v128 offset:36864
	v_mfma_f32_32x32x16_bf16 v[16:31], v[236:239], v[136:139], v[16:31]
	s_add_u32 m0, s78, 0x0
	v_mfma_f32_32x32x16_bf16 v[0:15], v[240:243], v[136:139], v[0:15]
	global_load_lds_dwordx4 v180, s[72:73]
	global_load_lds_dwordx4 v180, s[72:73] offset:1024
	v_mfma_f32_32x32x16_bf16 v[112:127], v[236:239], v[172:175], v[112:127]
	global_load_lds_dwordx4 v180, s[72:73] offset:2048
	global_load_lds_dwordx4 v180, s[72:73] offset:3072
	s_add_u32 m0, s79, 0x4000
	v_mfma_f32_32x32x16_bf16 v[96:111], v[240:243], v[172:175], v[96:111]
	global_load_lds_dwordx4 v181, s[74:75]
	global_load_lds_dwordx4 v181, s[74:75] offset:1024
	v_mfma_f32_32x32x16_bf16 v[48:63], v[236:239], v[176:179], v[48:63]
	s_add_u32 s72, s72, 0x202000
	s_addc_u32 s73, s73, 0
	v_mfma_f32_32x32x16_bf16 v[32:47], v[240:243], v[176:179], v[32:47]
	s_add_u32 s74, s74, 0x10000
	s_addc_u32 s75, s75, 0
	s_waitcnt lgkmcnt(0)
	ds_read_b128 v[236:239], v169 offset:24576
	ds_read_b128 v[240:243], v169 offset:26624
	v_mfma_f32_32x32x16_bf16 v[80:95], v[212:215], v[220:223], v[80:95]
	ds_read_b128 v[132:135], v129 offset:24576
	ds_read_b128 v[136:139], v129 offset:28672
	v_mfma_f32_32x32x16_bf16 v[64:79], v[216:219], v[220:223], v[64:79]
	ds_read_b128 v[172:175], v129 offset:32768
	ds_read_b128 v[176:179], v129 offset:36864
	v_mfma_f32_32x32x16_bf16 v[16:31], v[212:215], v[224:227], v[16:31]
	v_mfma_f32_32x32x16_bf16 v[0:15], v[216:219], v[224:227], v[0:15]
	v_mfma_f32_32x32x16_bf16 v[112:127], v[212:215], v[228:231], v[112:127]
	v_mfma_f32_32x32x16_bf16 v[96:111], v[216:219], v[228:231], v[96:111]
	v_mfma_f32_32x32x16_bf16 v[48:63], v[212:215], v[232:235], v[48:63]
	v_mfma_f32_32x32x16_bf16 v[32:47], v[216:219], v[232:235], v[32:47]
	s_waitcnt lgkmcnt(0)
	s_waitcnt vmcnt(6)
	s_barrier
	ds_read_b128 v[212:215], v167 offset:49152
	ds_read_b128 v[216:219], v167 offset:51200
	v_mfma_f32_32x32x16_bf16 v[80:95], v[236:239], v[132:135], v[80:95]
	ds_read_b128 v[220:223], v128 offset:49152
	ds_read_b128 v[224:227], v128 offset:53248
	v_mfma_f32_32x32x16_bf16 v[64:79], v[240:243], v[132:135], v[64:79]
	ds_read_b128 v[228:231], v128 offset:57344
	ds_read_b128 v[232:235], v128 offset:61440
	v_mfma_f32_32x32x16_bf16 v[16:31], v[236:239], v[136:139], v[16:31]
	s_add_u32 m0, s78, 0x6000
	v_mfma_f32_32x32x16_bf16 v[0:15], v[240:243], v[136:139], v[0:15]
	global_load_lds_dwordx4 v180, s[72:73]
	global_load_lds_dwordx4 v180, s[72:73] offset:1024
	v_mfma_f32_32x32x16_bf16 v[112:127], v[236:239], v[172:175], v[112:127]
	global_load_lds_dwordx4 v180, s[72:73] offset:2048
	global_load_lds_dwordx4 v180, s[72:73] offset:3072
	s_add_u32 m0, s79, 0xa000
	v_mfma_f32_32x32x16_bf16 v[96:111], v[240:243], v[172:175], v[96:111]
	global_load_lds_dwordx4 v181, s[74:75]
	global_load_lds_dwordx4 v181, s[74:75] offset:1024
	v_mfma_f32_32x32x16_bf16 v[48:63], v[236:239], v[176:179], v[48:63]
	s_add_u32 s72, s72, 0x202000
	s_addc_u32 s73, s73, 0
	v_mfma_f32_32x32x16_bf16 v[32:47], v[240:243], v[176:179], v[32:47]
	s_add_u32 s74, s74, 0x10000
	s_addc_u32 s75, s75, 0
	s_waitcnt lgkmcnt(0)
	ds_read_b128 v[236:239], v169 offset:49152
	ds_read_b128 v[240:243], v169 offset:51200
	v_mfma_f32_32x32x16_bf16 v[80:95], v[212:215], v[220:223], v[80:95]
	ds_read_b128 v[132:135], v129 offset:49152
	ds_read_b128 v[136:139], v129 offset:53248
	v_mfma_f32_32x32x16_bf16 v[64:79], v[216:219], v[220:223], v[64:79]
	ds_read_b128 v[172:175], v129 offset:57344
	ds_read_b128 v[176:179], v129 offset:61440
	v_mfma_f32_32x32x16_bf16 v[16:31], v[212:215], v[224:227], v[16:31]
	v_mfma_f32_32x32x16_bf16 v[0:15], v[216:219], v[224:227], v[0:15]
	v_mfma_f32_32x32x16_bf16 v[112:127], v[212:215], v[228:231], v[112:127]
	v_mfma_f32_32x32x16_bf16 v[96:111], v[216:219], v[228:231], v[96:111]
	v_mfma_f32_32x32x16_bf16 v[48:63], v[212:215], v[232:235], v[48:63]
	v_mfma_f32_32x32x16_bf16 v[32:47], v[216:219], v[232:235], v[32:47]
	s_waitcnt lgkmcnt(0)
	s_waitcnt vmcnt(6)
	s_barrier
	ds_read_b128 v[212:215], v167
	ds_read_b128 v[216:219], v167 offset:2048
	v_mfma_f32_32x32x16_bf16 v[80:95], v[236:239], v[132:135], v[80:95]
	ds_read_b128 v[220:223], v128
	ds_read_b128 v[224:227], v128 offset:4096
	v_mfma_f32_32x32x16_bf16 v[64:79], v[240:243], v[132:135], v[64:79]
	ds_read_b128 v[228:231], v128 offset:8192
	ds_read_b128 v[232:235], v128 offset:12288
	v_mfma_f32_32x32x16_bf16 v[16:31], v[236:239], v[136:139], v[16:31]
	v_mfma_f32_32x32x16_bf16 v[0:15], v[240:243], v[136:139], v[0:15]
	v_mfma_f32_32x32x16_bf16 v[112:127], v[236:239], v[172:175], v[112:127]
	v_mfma_f32_32x32x16_bf16 v[96:111], v[240:243], v[172:175], v[96:111]
	v_mfma_f32_32x32x16_bf16 v[48:63], v[236:239], v[176:179], v[48:63]
	v_mfma_f32_32x32x16_bf16 v[32:47], v[240:243], v[176:179], v[32:47]
	s_waitcnt lgkmcnt(0)
	ds_read_b128 v[236:239], v169
	ds_read_b128 v[240:243], v169 offset:2048
	v_mfma_f32_32x32x16_bf16 v[80:95], v[212:215], v[220:223], v[80:95]
	ds_read_b128 v[132:135], v129
	ds_read_b128 v[136:139], v129 offset:4096
	v_mfma_f32_32x32x16_bf16 v[64:79], v[216:219], v[220:223], v[64:79]
	ds_read_b128 v[172:175], v129 offset:8192
	ds_read_b128 v[176:179], v129 offset:12288
	v_mfma_f32_32x32x16_bf16 v[16:31], v[212:215], v[224:227], v[16:31]
	v_mfma_f32_32x32x16_bf16 v[0:15], v[216:219], v[224:227], v[0:15]
	v_mfma_f32_32x32x16_bf16 v[112:127], v[212:215], v[228:231], v[112:127]
	v_mfma_f32_32x32x16_bf16 v[96:111], v[216:219], v[228:231], v[96:111]
	v_mfma_f32_32x32x16_bf16 v[48:63], v[212:215], v[232:235], v[48:63]
	v_mfma_f32_32x32x16_bf16 v[32:47], v[216:219], v[232:235], v[32:47]
	s_waitcnt lgkmcnt(0)
	s_waitcnt vmcnt(0)
	s_barrier
	ds_read_b128 v[212:215], v167 offset:24576
	ds_read_b128 v[216:219], v167 offset:26624
	v_mfma_f32_32x32x16_bf16 v[80:95], v[236:239], v[132:135], v[80:95]
	ds_read_b128 v[220:223], v128 offset:24576
	ds_read_b128 v[224:227], v128 offset:28672
	v_mfma_f32_32x32x16_bf16 v[64:79], v[240:243], v[132:135], v[64:79]
	ds_read_b128 v[228:231], v128 offset:32768
	ds_read_b128 v[232:235], v128 offset:36864
	v_mfma_f32_32x32x16_bf16 v[16:31], v[236:239], v[136:139], v[16:31]
	v_mfma_f32_32x32x16_bf16 v[0:15], v[240:243], v[136:139], v[0:15]
	v_mfma_f32_32x32x16_bf16 v[112:127], v[236:239], v[172:175], v[112:127]
	v_mfma_f32_32x32x16_bf16 v[96:111], v[240:243], v[172:175], v[96:111]
	v_mfma_f32_32x32x16_bf16 v[48:63], v[236:239], v[176:179], v[48:63]
	v_mfma_f32_32x32x16_bf16 v[32:47], v[240:243], v[176:179], v[32:47]
	s_waitcnt lgkmcnt(0)
	ds_read_b128 v[236:239], v169 offset:24576
	ds_read_b128 v[240:243], v169 offset:26624
	v_mfma_f32_32x32x16_bf16 v[80:95], v[212:215], v[220:223], v[80:95]
	ds_read_b128 v[132:135], v129 offset:24576
	ds_read_b128 v[136:139], v129 offset:28672
	v_mfma_f32_32x32x16_bf16 v[64:79], v[216:219], v[220:223], v[64:79]
	ds_read_b128 v[172:175], v129 offset:32768
	ds_read_b128 v[176:179], v129 offset:36864
	v_mfma_f32_32x32x16_bf16 v[16:31], v[212:215], v[224:227], v[16:31]
	v_mfma_f32_32x32x16_bf16 v[0:15], v[216:219], v[224:227], v[0:15]
	v_mfma_f32_32x32x16_bf16 v[112:127], v[212:215], v[228:231], v[112:127]
	v_mfma_f32_32x32x16_bf16 v[96:111], v[216:219], v[228:231], v[96:111]
	v_mfma_f32_32x32x16_bf16 v[48:63], v[212:215], v[232:235], v[48:63]
	v_mfma_f32_32x32x16_bf16 v[32:47], v[216:219], v[232:235], v[32:47]
	s_waitcnt lgkmcnt(0)
	v_mfma_f32_32x32x16_bf16 v[80:95], v[236:239], v[132:135], v[80:95]
	v_mfma_f32_32x32x16_bf16 v[64:79], v[240:243], v[132:135], v[64:79]
	v_mfma_f32_32x32x16_bf16 v[16:31], v[236:239], v[136:139], v[16:31]
	v_mfma_f32_32x32x16_bf16 v[0:15], v[240:243], v[136:139], v[0:15]
	v_mfma_f32_32x32x16_bf16 v[112:127], v[236:239], v[172:175], v[112:127]
	v_mfma_f32_32x32x16_bf16 v[96:111], v[240:243], v[172:175], v[96:111]
	v_mfma_f32_32x32x16_bf16 v[48:63], v[236:239], v[176:179], v[48:63]
	v_mfma_f32_32x32x16_bf16 v[32:47], v[240:243], v[176:179], v[32:47]
	s_nop 15
	v_readlane_b32 s72, v254, 13
	v_readlane_b32 s73, v254, 14
	s_nop 1
	v_mov_b64_e32 v[130:131], s[72:73]

.LBB0_630:
	s_or_saveexec_b64 s[0:1], s[0:1]
	v_mov_b32_e32 v63, 0
	v_mov_b32_e32 v62, 0
	v_mov_b32_e32 v61, 0
	v_mov_b32_e32 v60, 0
	v_mov_b32_e32 v59, 0
	v_mov_b32_e32 v58, 0
	v_mov_b32_e32 v57, 0
	v_mov_b32_e32 v56, 0
	v_mov_b32_e32 v55, 0
	v_mov_b32_e32 v54, 0
	v_mov_b32_e32 v53, 0
	v_mov_b32_e32 v52, 0
	v_mov_b32_e32 v51, 0
	v_mov_b32_e32 v50, 0
	v_mov_b32_e32 v49, 0
	v_mov_b32_e32 v48, v63
	v_mov_b32_e32 v31, 0
	v_mov_b32_e32 v30, 0
	v_mov_b32_e32 v29, 0
	v_mov_b32_e32 v28, 0
	v_mov_b32_e32 v27, 0
	v_mov_b32_e32 v26, 0
	v_mov_b32_e32 v25, 0
	v_mov_b32_e32 v24, 0
	v_mov_b32_e32 v23, 0
	v_mov_b32_e32 v22, 0
	v_mov_b32_e32 v21, 0
	v_mov_b32_e32 v20, 0
	v_mov_b32_e32 v19, 0
	v_mov_b32_e32 v18, 0
	v_mov_b32_e32 v17, 0
	v_mov_b32_e32 v16, v63
	v_mov_b32_e32 v47, 0
	v_mov_b32_e32 v46, v63
	v_mov_b32_e32 v45, 0
	v_mov_b32_e32 v44, v63
	v_mov_b32_e32 v43, 0
	v_mov_b32_e32 v42, v63
	v_mov_b32_e32 v41, 0
	v_mov_b32_e32 v40, v63
	v_mov_b32_e32 v39, 0
	v_mov_b32_e32 v38, v63
	v_mov_b32_e32 v37, 0
	v_mov_b32_e32 v36, 0
	v_mov_b32_e32 v35, 0
	v_mov_b32_e32 v34, 0
	v_mov_b32_e32 v33, 0
	v_mov_b32_e32 v32, v63
	v_mov_b32_e32 v15, 0
	v_mov_b32_e32 v14, v63
	v_mov_b32_e32 v13, 0
	v_mov_b32_e32 v12, v63
	v_mov_b32_e32 v11, 0
	v_mov_b32_e32 v10, v63
	v_mov_b32_e32 v9, 0
	v_mov_b32_e32 v8, v63
	v_mov_b32_e32 v7, 0
	v_mov_b32_e32 v6, v63
	v_mov_b32_e32 v5, 0
	v_mov_b32_e32 v4, 0
	v_mov_b32_e32 v3, 0
	v_mov_b32_e32 v2, 0
	v_mov_b32_e32 v1, 0
	v_mov_b32_e32 v0, v63
	s_xor_b64 exec, exec, s[0:1]
	s_cbranch_execz .LBB0_634
	v_readfirstlane_b32 s10, v128
	v_readfirstlane_b32 s11, v130
	v_readfirstlane_b32 s8, v226
	v_mbcnt_lo_u32_b32 v192, -1, 0
	v_mbcnt_hi_u32_b32 v192, -1, v192
	s_nop 3
	s_lshl_b32 s10, s10, 14
	s_lshl_b32 s11, s11, 13
	s_add_u32 s4, s90, s10
	s_addc_u32 s5, s91, 0
	s_add_u32 s6, s90, s11
	s_addc_u32 s7, s91, 0
	s_add_u32 s6, s6, 0x1b3c8000
	s_addc_u32 s7, s7, 0
	v_and_b32_e32 v193, 31, v192
	v_lshrrev_b32_e32 v194, 5, v192
	v_bfe_u32 v195, v192, 2, 2
	v_xor_b32_e32 v194, v194, v195
	v_lshlrev_b32_e32 v194, 4, v194
	v_lshl_or_b32 v193, v193, 6, v194
	v_lshrrev_b32_e32 v195, 10, v226
	v_lshrrev_b32_e32 v194, 1, v195
	v_lshl_or_b32 v129, v194, 11, v193
	v_and_b32_e32 v194, 1, v195
	v_lshl_or_b32 v156, v194, 12, v193
	v_or_b32_e32 v156, 0x4000, v156
	v_xor_b32_e32 v131, 32, v129
	v_xor_b32_e32 v188, 32, v156
	v_lshrrev_b32_e32 v193, 2, v192
	v_lshrrev_b32_e32 v194, 4, v192
	v_xor_b32_e32 v194, v194, v192
	v_and_b32_e32 v194, 3, v194
	v_lshlrev_b32_e32 v194, 4, v194
	v_lshl_or_b32 v193, v193, 6, v194
	v_or_b32_e32 v189, v193, v226
	v_add_u32_e32 v252, 0x1000, v189
	v_add_u32_e32 v190, 0x2000, v189
	v_add_u32_e32 v191, 0x3000, v189
	s_add_u32 m0, s8, 0x2000
	s_nop 0
	global_load_lds_dwordx4 v190, s[4:5]
	s_add_u32 m0, s8, 0x3000
	s_nop 0
	global_load_lds_dwordx4 v191, s[4:5]
	s_add_u32 m0, s8, 0x4000
	s_nop 0
	global_load_lds_dwordx4 v189, s[6:7]
	s_add_u32 m0, s8, 0x5000
	s_nop 0
	global_load_lds_dwordx4 v252, s[6:7]
	s_add_u32 s4, s4, 0x202000
	s_addc_u32 s5, s5, 0
	s_add_u32 s6, s6, 0x40000
	s_addc_u32 s7, s7, 0
	s_lshl_b32 s10, s8, 2
	s_lshl_b32 s11, s8, 1
	v_sub_u32_e32 v190, v189, v226
	v_lshl_add_u32 v191, v226, 1, v190
	v_lshl_add_u32 v190, v226, 2, v190
	s_add_u32 m0, s10, 0x6000
	s_nop 0
	global_load_lds_dwordx4 v190, s[4:5]
	global_load_lds_dwordx4 v190, s[4:5] offset:1024
	global_load_lds_dwordx4 v190, s[4:5] offset:2048
	global_load_lds_dwordx4 v190, s[4:5] offset:3072
	s_add_u32 m0, s11, 0xa000
	s_nop 0
	global_load_lds_dwordx4 v191, s[6:7]
	global_load_lds_dwordx4 v191, s[6:7] offset:1024
	s_add_u32 s4, s4, 0x202000
	s_addc_u32 s5, s5, 0
	s_add_u32 s6, s6, 0x40000
	s_addc_u32 s7, s7, 0
	s_add_u32 m0, s10, 0xc000
	s_nop 0
	global_load_lds_dwordx4 v190, s[4:5]
	global_load_lds_dwordx4 v190, s[4:5] offset:1024
	global_load_lds_dwordx4 v190, s[4:5] offset:2048
	global_load_lds_dwordx4 v190, s[4:5] offset:3072
	s_add_u32 m0, s11, 0x10000
	s_nop 0
	global_load_lds_dwordx4 v191, s[6:7]
	global_load_lds_dwordx4 v191, s[6:7] offset:1024
	s_add_u32 s4, s4, 0x202000
	s_addc_u32 s5, s5, 0
	s_add_u32 s6, s6, 0x40000
	s_addc_u32 s7, s7, 0
	s_waitcnt vmcnt(12)
	s_barrier
	ds_read_b128 v[132:135], v156
	ds_read_b128 v[136:139], v156 offset:2048
	ds_read_b128 v[140:143], v129
	ds_read_b128 v[180:183], v129 offset:4096
	ds_read_b128 v[184:187], v129 offset:8192
	ds_read_b128 v[236:239], v129 offset:12288
	s_waitcnt lgkmcnt(0)
	ds_read_b128 v[240:243], v188
	ds_read_b128 v[244:247], v188 offset:2048
	v_mfma_f32_32x32x16_bf16 v[112:127], v[132:135], v[140:143], 0
	ds_read_b128 v[248:251], v131
	ds_read_b128 v[200:203], v131 offset:4096
	v_mfma_f32_32x32x16_bf16 v[96:111], v[136:139], v[140:143], 0
	ds_read_b128 v[204:207], v131 offset:8192
	ds_read_b128 v[208:211], v131 offset:12288
	v_mfma_f32_32x32x16_bf16 v[80:95], v[132:135], v[180:183], 0
	v_mfma_f32_32x32x16_bf16 v[64:79], v[136:139], v[180:183], 0
	v_mfma_f32_32x32x16_bf16 v[48:63], v[132:135], v[184:187], 0
	v_mfma_f32_32x32x16_bf16 v[32:47], v[136:139], v[184:187], 0
	v_mfma_f32_32x32x16_bf16 v[16:31], v[132:135], v[236:239], 0
	v_mfma_f32_32x32x16_bf16 v[0:15], v[136:139], v[236:239], 0
	s_waitcnt lgkmcnt(0)
	s_waitcnt vmcnt(6)
	s_barrier
	ds_read_b128 v[132:135], v156 offset:24576
	ds_read_b128 v[136:139], v156 offset:26624
	v_mfma_f32_32x32x16_bf16 v[112:127], v[240:243], v[248:251], v[112:127]
	ds_read_b128 v[140:143], v129 offset:24576
	ds_read_b128 v[180:183], v129 offset:28672
	v_mfma_f32_32x32x16_bf16 v[96:111], v[244:247], v[248:251], v[96:111]
	ds_read_b128 v[184:187], v129 offset:32768
	ds_read_b128 v[236:239], v129 offset:36864
	v_mfma_f32_32x32x16_bf16 v[80:95], v[240:243], v[200:203], v[80:95]
	s_add_u32 m0, s10, 0x0
	v_mfma_f32_32x32x16_bf16 v[64:79], v[244:247], v[200:203], v[64:79]
	global_load_lds_dwordx4 v190, s[4:5]
	global_load_lds_dwordx4 v190, s[4:5] offset:1024
	v_mfma_f32_32x32x16_bf16 v[48:63], v[240:243], v[204:207], v[48:63]
	global_load_lds_dwordx4 v190, s[4:5] offset:2048
	global_load_lds_dwordx4 v190, s[4:5] offset:3072
	s_add_u32 m0, s11, 0x4000
	v_mfma_f32_32x32x16_bf16 v[32:47], v[244:247], v[204:207], v[32:47]
	global_load_lds_dwordx4 v191, s[6:7]
	global_load_lds_dwordx4 v191, s[6:7] offset:1024
	v_mfma_f32_32x32x16_bf16 v[16:31], v[240:243], v[208:211], v[16:31]
	s_add_u32 s4, s4, 0x202000
	s_addc_u32 s5, s5, 0
	v_mfma_f32_32x32x16_bf16 v[0:15], v[244:247], v[208:211], v[0:15]
	s_add_u32 s6, s6, 0x40000
	s_addc_u32 s7, s7, 0
	s_waitcnt lgkmcnt(0)
	ds_read_b128 v[240:243], v188 offset:24576
	ds_read_b128 v[244:247], v188 offset:26624
	v_mfma_f32_32x32x16_bf16 v[112:127], v[132:135], v[140:143], v[112:127]
	ds_read_b128 v[248:251], v131 offset:24576
	ds_read_b128 v[200:203], v131 offset:28672
	v_mfma_f32_32x32x16_bf16 v[96:111], v[136:139], v[140:143], v[96:111]
	ds_read_b128 v[204:207], v131 offset:32768
	ds_read_b128 v[208:211], v131 offset:36864
	v_mfma_f32_32x32x16_bf16 v[80:95], v[132:135], v[180:183], v[80:95]
	v_mfma_f32_32x32x16_bf16 v[64:79], v[136:139], v[180:183], v[64:79]
	v_mfma_f32_32x32x16_bf16 v[48:63], v[132:135], v[184:187], v[48:63]
	v_mfma_f32_32x32x16_bf16 v[32:47], v[136:139], v[184:187], v[32:47]
	v_mfma_f32_32x32x16_bf16 v[16:31], v[132:135], v[236:239], v[16:31]
	v_mfma_f32_32x32x16_bf16 v[0:15], v[136:139], v[236:239], v[0:15]
	s_waitcnt lgkmcnt(0)
	s_waitcnt vmcnt(6)
	s_barrier
	ds_read_b128 v[132:135], v156 offset:49152
	ds_read_b128 v[136:139], v156 offset:51200
	v_mfma_f32_32x32x16_bf16 v[112:127], v[240:243], v[248:251], v[112:127]
	ds_read_b128 v[140:143], v129 offset:49152
	ds_read_b128 v[180:183], v129 offset:53248
	v_mfma_f32_32x32x16_bf16 v[96:111], v[244:247], v[248:251], v[96:111]
	ds_read_b128 v[184:187], v129 offset:57344
	ds_read_b128 v[236:239], v129 offset:61440
	v_mfma_f32_32x32x16_bf16 v[80:95], v[240:243], v[200:203], v[80:95]
	s_add_u32 m0, s10, 0x6000
	v_mfma_f32_32x32x16_bf16 v[64:79], v[244:247], v[200:203], v[64:79]
	global_load_lds_dwordx4 v190, s[4:5]
	global_load_lds_dwordx4 v190, s[4:5] offset:1024
	v_mfma_f32_32x32x16_bf16 v[48:63], v[240:243], v[204:207], v[48:63]
	global_load_lds_dwordx4 v190, s[4:5] offset:2048
	global_load_lds_dwordx4 v190, s[4:5] offset:3072
	s_add_u32 m0, s11, 0xa000
	v_mfma_f32_32x32x16_bf16 v[32:47], v[244:247], v[204:207], v[32:47]
	global_load_lds_dwordx4 v191, s[6:7]
	global_load_lds_dwordx4 v191, s[6:7] offset:1024
	v_mfma_f32_32x32x16_bf16 v[16:31], v[240:243], v[208:211], v[16:31]
	s_add_u32 s4, s4, 0x202000
	s_addc_u32 s5, s5, 0
	v_mfma_f32_32x32x16_bf16 v[0:15], v[244:247], v[208:211], v[0:15]
	s_add_u32 s6, s6, 0x40000
	s_addc_u32 s7, s7, 0
	s_waitcnt lgkmcnt(0)
	ds_read_b128 v[240:243], v188 offset:49152
	ds_read_b128 v[244:247], v188 offset:51200
	v_mfma_f32_32x32x16_bf16 v[112:127], v[132:135], v[140:143], v[112:127]
	ds_read_b128 v[248:251], v131 offset:49152
	ds_read_b128 v[200:203], v131 offset:53248
	v_mfma_f32_32x32x16_bf16 v[96:111], v[136:139], v[140:143], v[96:111]
	ds_read_b128 v[204:207], v131 offset:57344
	ds_read_b128 v[208:211], v131 offset:61440
	v_mfma_f32_32x32x16_bf16 v[80:95], v[132:135], v[180:183], v[80:95]
	v_mfma_f32_32x32x16_bf16 v[64:79], v[136:139], v[180:183], v[64:79]
	v_mfma_f32_32x32x16_bf16 v[48:63], v[132:135], v[184:187], v[48:63]
	v_mfma_f32_32x32x16_bf16 v[32:47], v[136:139], v[184:187], v[32:47]
	v_mfma_f32_32x32x16_bf16 v[16:31], v[132:135], v[236:239], v[16:31]
	v_mfma_f32_32x32x16_bf16 v[0:15], v[136:139], v[236:239], v[0:15]
	s_waitcnt lgkmcnt(0)
	s_waitcnt vmcnt(6)
	s_barrier
	ds_read_b128 v[132:135], v156
	ds_read_b128 v[136:139], v156 offset:2048
	v_mfma_f32_32x32x16_bf16 v[112:127], v[240:243], v[248:251], v[112:127]
	ds_read_b128 v[140:143], v129
	ds_read_b128 v[180:183], v129 offset:4096
	v_mfma_f32_32x32x16_bf16 v[96:111], v[244:247], v[248:251], v[96:111]
	ds_read_b128 v[184:187], v129 offset:8192
	ds_read_b128 v[236:239], v129 offset:12288
	v_mfma_f32_32x32x16_bf16 v[80:95], v[240:243], v[200:203], v[80:95]
	s_add_u32 m0, s10, 0xc000
	v_mfma_f32_32x32x16_bf16 v[64:79], v[244:247], v[200:203], v[64:79]
	global_load_lds_dwordx4 v190, s[4:5]
	global_load_lds_dwordx4 v190, s[4:5] offset:1024
	v_mfma_f32_32x32x16_bf16 v[48:63], v[240:243], v[204:207], v[48:63]
	global_load_lds_dwordx4 v190, s[4:5] offset:2048
	global_load_lds_dwordx4 v190, s[4:5] offset:3072
	s_add_u32 m0, s11, 0x10000
	v_mfma_f32_32x32x16_bf16 v[32:47], v[244:247], v[204:207], v[32:47]
	global_load_lds_dwordx4 v191, s[6:7]
	global_load_lds_dwordx4 v191, s[6:7] offset:1024
	v_mfma_f32_32x32x16_bf16 v[16:31], v[240:243], v[208:211], v[16:31]
	s_add_u32 s4, s4, 0x202000
	s_addc_u32 s5, s5, 0
	v_mfma_f32_32x32x16_bf16 v[0:15], v[244:247], v[208:211], v[0:15]
	s_add_u32 s6, s6, 0x40000
	s_addc_u32 s7, s7, 0
	s_waitcnt lgkmcnt(0)
	s_mov_b32 s9, 8
.Lgemm_p4_loop:
	ds_read_b128 v[240:243], v188
	ds_read_b128 v[244:247], v188 offset:2048
	v_mfma_f32_32x32x16_bf16 v[112:127], v[132:135], v[140:143], v[112:127]
	ds_read_b128 v[248:251], v131
	ds_read_b128 v[200:203], v131 offset:4096
	v_mfma_f32_32x32x16_bf16 v[96:111], v[136:139], v[140:143], v[96:111]
	ds_read_b128 v[204:207], v131 offset:8192
	ds_read_b128 v[208:211], v131 offset:12288
	v_mfma_f32_32x32x16_bf16 v[80:95], v[132:135], v[180:183], v[80:95]
	v_mfma_f32_32x32x16_bf16 v[64:79], v[136:139], v[180:183], v[64:79]
	v_mfma_f32_32x32x16_bf16 v[48:63], v[132:135], v[184:187], v[48:63]
	v_mfma_f32_32x32x16_bf16 v[32:47], v[136:139], v[184:187], v[32:47]
	v_mfma_f32_32x32x16_bf16 v[16:31], v[132:135], v[236:239], v[16:31]
	v_mfma_f32_32x32x16_bf16 v[0:15], v[136:139], v[236:239], v[0:15]
	s_waitcnt lgkmcnt(0)
	s_waitcnt vmcnt(6)
	s_barrier
	ds_read_b128 v[132:135], v156 offset:24576
	ds_read_b128 v[136:139], v156 offset:26624
	v_mfma_f32_32x32x16_bf16 v[112:127], v[240:243], v[248:251], v[112:127]
	ds_read_b128 v[140:143], v129 offset:24576
	ds_read_b128 v[180:183], v129 offset:28672
	v_mfma_f32_32x32x16_bf16 v[96:111], v[244:247], v[248:251], v[96:111]
	ds_read_b128 v[184:187], v129 offset:32768
	ds_read_b128 v[236:239], v129 offset:36864
	v_mfma_f32_32x32x16_bf16 v[80:95], v[240:243], v[200:203], v[80:95]
	s_add_u32 m0, s10, 0x0
	v_mfma_f32_32x32x16_bf16 v[64:79], v[244:247], v[200:203], v[64:79]
	global_load_lds_dwordx4 v190, s[4:5]
	global_load_lds_dwordx4 v190, s[4:5] offset:1024
	v_mfma_f32_32x32x16_bf16 v[48:63], v[240:243], v[204:207], v[48:63]
	global_load_lds_dwordx4 v190, s[4:5] offset:2048
	global_load_lds_dwordx4 v190, s[4:5] offset:3072
	s_add_u32 m0, s11, 0x4000
	v_mfma_f32_32x32x16_bf16 v[32:47], v[244:247], v[204:207], v[32:47]
	global_load_lds_dwordx4 v191, s[6:7]
	global_load_lds_dwordx4 v191, s[6:7] offset:1024
	v_mfma_f32_32x32x16_bf16 v[16:31], v[240:243], v[208:211], v[16:31]
	s_add_u32 s4, s4, 0x202000
	s_addc_u32 s5, s5, 0
	v_mfma_f32_32x32x16_bf16 v[0:15], v[244:247], v[208:211], v[0:15]
	s_add_u32 s6, s6, 0x40000
	s_addc_u32 s7, s7, 0
	s_waitcnt lgkmcnt(0)
	ds_read_b128 v[240:243], v188 offset:24576
	ds_read_b128 v[244:247], v188 offset:26624
	v_mfma_f32_32x32x16_bf16 v[112:127], v[132:135], v[140:143], v[112:127]
	ds_read_b128 v[248:251], v131 offset:24576
	ds_read_b128 v[200:203], v131 offset:28672
	v_mfma_f32_32x32x16_bf16 v[96:111], v[136:139], v[140:143], v[96:111]
	ds_read_b128 v[204:207], v131 offset:32768
	ds_read_b128 v[208:211], v131 offset:36864
	v_mfma_f32_32x32x16_bf16 v[80:95], v[132:135], v[180:183], v[80:95]
	v_mfma_f32_32x32x16_bf16 v[64:79], v[136:139], v[180:183], v[64:79]
	v_mfma_f32_32x32x16_bf16 v[48:63], v[132:135], v[184:187], v[48:63]
	v_mfma_f32_32x32x16_bf16 v[32:47], v[136:139], v[184:187], v[32:47]
	v_mfma_f32_32x32x16_bf16 v[16:31], v[132:135], v[236:239], v[16:31]
	v_mfma_f32_32x32x16_bf16 v[0:15], v[136:139], v[236:239], v[0:15]
	s_waitcnt lgkmcnt(0)
	s_waitcnt vmcnt(6)
	s_barrier
	ds_read_b128 v[132:135], v156 offset:49152
	ds_read_b128 v[136:139], v156 offset:51200
	v_mfma_f32_32x32x16_bf16 v[112:127], v[240:243], v[248:251], v[112:127]
	ds_read_b128 v[140:143], v129 offset:49152
	ds_read_b128 v[180:183], v129 offset:53248
	v_mfma_f32_32x32x16_bf16 v[96:111], v[244:247], v[248:251], v[96:111]
	ds_read_b128 v[184:187], v129 offset:57344
	ds_read_b128 v[236:239], v129 offset:61440
	v_mfma_f32_32x32x16_bf16 v[80:95], v[240:243], v[200:203], v[80:95]
	s_add_u32 m0, s10, 0x6000
	v_mfma_f32_32x32x16_bf16 v[64:79], v[244:247], v[200:203], v[64:79]
	global_load_lds_dwordx4 v190, s[4:5]
	global_load_lds_dwordx4 v190, s[4:5] offset:1024
	v_mfma_f32_32x32x16_bf16 v[48:63], v[240:243], v[204:207], v[48:63]
	global_load_lds_dwordx4 v190, s[4:5] offset:2048
	global_load_lds_dwordx4 v190, s[4:5] offset:3072
	s_add_u32 m0, s11, 0xa000
	v_mfma_f32_32x32x16_bf16 v[32:47], v[244:247], v[204:207], v[32:47]
	global_load_lds_dwordx4 v191, s[6:7]
	global_load_lds_dwordx4 v191, s[6:7] offset:1024
	v_mfma_f32_32x32x16_bf16 v[16:31], v[240:243], v[208:211], v[16:31]
	s_add_u32 s4, s4, 0x202000
	s_addc_u32 s5, s5, 0
	v_mfma_f32_32x32x16_bf16 v[0:15], v[244:247], v[208:211], v[0:15]
	s_add_u32 s6, s6, 0x40000
	s_addc_u32 s7, s7, 0
	s_waitcnt lgkmcnt(0)
	ds_read_b128 v[240:243], v188 offset:49152
	ds_read_b128 v[244:247], v188 offset:51200
	v_mfma_f32_32x32x16_bf16 v[112:127], v[132:135], v[140:143], v[112:127]
	ds_read_b128 v[248:251], v131 offset:49152
	ds_read_b128 v[200:203], v131 offset:53248
	v_mfma_f32_32x32x16_bf16 v[96:111], v[136:139], v[140:143], v[96:111]
	ds_read_b128 v[204:207], v131 offset:57344
	ds_read_b128 v[208:211], v131 offset:61440
	v_mfma_f32_32x32x16_bf16 v[80:95], v[132:135], v[180:183], v[80:95]
	v_mfma_f32_32x32x16_bf16 v[64:79], v[136:139], v[180:183], v[64:79]
	v_mfma_f32_32x32x16_bf16 v[48:63], v[132:135], v[184:187], v[48:63]
	v_mfma_f32_32x32x16_bf16 v[32:47], v[136:139], v[184:187], v[32:47]
	v_mfma_f32_32x32x16_bf16 v[16:31], v[132:135], v[236:239], v[16:31]
	v_mfma_f32_32x32x16_bf16 v[0:15], v[136:139], v[236:239], v[0:15]
	s_waitcnt lgkmcnt(0)
	s_waitcnt vmcnt(6)
	s_barrier
	ds_read_b128 v[132:135], v156
	ds_read_b128 v[136:139], v156 offset:2048
	v_mfma_f32_32x32x16_bf16 v[112:127], v[240:243], v[248:251], v[112:127]
	ds_read_b128 v[140:143], v129
	ds_read_b128 v[180:183], v129 offset:4096
	v_mfma_f32_32x32x16_bf16 v[96:111], v[244:247], v[248:251], v[96:111]
	ds_read_b128 v[184:187], v129 offset:8192
	ds_read_b128 v[236:239], v129 offset:12288
	v_mfma_f32_32x32x16_bf16 v[80:95], v[240:243], v[200:203], v[80:95]
	s_add_u32 m0, s10, 0xc000
	v_mfma_f32_32x32x16_bf16 v[64:79], v[244:247], v[200:203], v[64:79]
	global_load_lds_dwordx4 v190, s[4:5]
	global_load_lds_dwordx4 v190, s[4:5] offset:1024
	v_mfma_f32_32x32x16_bf16 v[48:63], v[240:243], v[204:207], v[48:63]
	global_load_lds_dwordx4 v190, s[4:5] offset:2048
	global_load_lds_dwordx4 v190, s[4:5] offset:3072
	s_add_u32 m0, s11, 0x10000
	v_mfma_f32_32x32x16_bf16 v[32:47], v[244:247], v[204:207], v[32:47]
	global_load_lds_dwordx4 v191, s[6:7]
	global_load_lds_dwordx4 v191, s[6:7] offset:1024
	v_mfma_f32_32x32x16_bf16 v[16:31], v[240:243], v[208:211], v[16:31]
	s_add_u32 s4, s4, 0x202000
	s_addc_u32 s5, s5, 0
	v_mfma_f32_32x32x16_bf16 v[0:15], v[244:247], v[208:211], v[0:15]
	s_add_u32 s6, s6, 0x40000
	s_addc_u32 s7, s7, 0
	s_waitcnt lgkmcnt(0)
	s_sub_i32 s9, s9, 1
	s_cmp_lg_u32 s9, 0
	s_cbranch_scc1 .Lgemm_p4_loop
	ds_read_b128 v[240:243], v188
	ds_read_b128 v[244:247], v188 offset:2048
	v_mfma_f32_32x32x16_bf16 v[112:127], v[132:135], v[140:143], v[112:127]
	ds_read_b128 v[248:251], v131
	ds_read_b128 v[200:203], v131 offset:4096
	v_mfma_f32_32x32x16_bf16 v[96:111], v[136:139], v[140:143], v[96:111]
	ds_read_b128 v[204:207], v131 offset:8192
	ds_read_b128 v[208:211], v131 offset:12288
	v_mfma_f32_32x32x16_bf16 v[80:95], v[132:135], v[180:183], v[80:95]
	v_mfma_f32_32x32x16_bf16 v[64:79], v[136:139], v[180:183], v[64:79]
	v_mfma_f32_32x32x16_bf16 v[48:63], v[132:135], v[184:187], v[48:63]
	v_mfma_f32_32x32x16_bf16 v[32:47], v[136:139], v[184:187], v[32:47]
	v_mfma_f32_32x32x16_bf16 v[16:31], v[132:135], v[236:239], v[16:31]
	v_mfma_f32_32x32x16_bf16 v[0:15], v[136:139], v[236:239], v[0:15]
	s_waitcnt lgkmcnt(0)
	s_waitcnt vmcnt(6)
	s_barrier
	ds_read_b128 v[132:135], v156 offset:24576
	ds_read_b128 v[136:139], v156 offset:26624
	v_mfma_f32_32x32x16_bf16 v[112:127], v[240:243], v[248:251], v[112:127]
	ds_read_b128 v[140:143], v129 offset:24576
	ds_read_b128 v[180:183], v129 offset:28672
	v_mfma_f32_32x32x16_bf16 v[96:111], v[244:247], v[248:251], v[96:111]
	ds_read_b128 v[184:187], v129 offset:32768
	ds_read_b128 v[236:239], v129 offset:36864
	v_mfma_f32_32x32x16_bf16 v[80:95], v[240:243], v[200:203], v[80:95]
	s_add_u32 m0, s10, 0x0
	v_mfma_f32_32x32x16_bf16 v[64:79], v[244:247], v[200:203], v[64:79]
	global_load_lds_dwordx4 v190, s[4:5]
	global_load_lds_dwordx4 v190, s[4:5] offset:1024
	v_mfma_f32_32x32x16_bf16 v[48:63], v[240:243], v[204:207], v[48:63]
	global_load_lds_dwordx4 v190, s[4:5] offset:2048
	global_load_lds_dwordx4 v190, s[4:5] offset:3072
	s_add_u32 m0, s11, 0x4000
	v_mfma_f32_32x32x16_bf16 v[32:47], v[244:247], v[204:207], v[32:47]
	global_load_lds_dwordx4 v191, s[6:7]
	global_load_lds_dwordx4 v191, s[6:7] offset:1024
	v_mfma_f32_32x32x16_bf16 v[16:31], v[240:243], v[208:211], v[16:31]
	s_add_u32 s4, s4, 0x202000
	s_addc_u32 s5, s5, 0
	v_mfma_f32_32x32x16_bf16 v[0:15], v[244:247], v[208:211], v[0:15]
	s_add_u32 s6, s6, 0x40000
	s_addc_u32 s7, s7, 0
	s_waitcnt lgkmcnt(0)
	ds_read_b128 v[240:243], v188 offset:24576
	ds_read_b128 v[244:247], v188 offset:26624
	v_mfma_f32_32x32x16_bf16 v[112:127], v[132:135], v[140:143], v[112:127]
	ds_read_b128 v[248:251], v131 offset:24576
	ds_read_b128 v[200:203], v131 offset:28672
	v_mfma_f32_32x32x16_bf16 v[96:111], v[136:139], v[140:143], v[96:111]
	ds_read_b128 v[204:207], v131 offset:32768
	ds_read_b128 v[208:211], v131 offset:36864
	v_mfma_f32_32x32x16_bf16 v[80:95], v[132:135], v[180:183], v[80:95]
	v_mfma_f32_32x32x16_bf16 v[64:79], v[136:139], v[180:183], v[64:79]
	v_mfma_f32_32x32x16_bf16 v[48:63], v[132:135], v[184:187], v[48:63]
	v_mfma_f32_32x32x16_bf16 v[32:47], v[136:139], v[184:187], v[32:47]
	v_mfma_f32_32x32x16_bf16 v[16:31], v[132:135], v[236:239], v[16:31]
	v_mfma_f32_32x32x16_bf16 v[0:15], v[136:139], v[236:239], v[0:15]
	s_waitcnt lgkmcnt(0)
	s_waitcnt vmcnt(6)
	s_barrier
	ds_read_b128 v[132:135], v156 offset:49152
	ds_read_b128 v[136:139], v156 offset:51200
	v_mfma_f32_32x32x16_bf16 v[112:127], v[240:243], v[248:251], v[112:127]
	ds_read_b128 v[140:143], v129 offset:49152
	ds_read_b128 v[180:183], v129 offset:53248
	v_mfma_f32_32x32x16_bf16 v[96:111], v[244:247], v[248:251], v[96:111]
	ds_read_b128 v[184:187], v129 offset:57344
	ds_read_b128 v[236:239], v129 offset:61440
	v_mfma_f32_32x32x16_bf16 v[80:95], v[240:243], v[200:203], v[80:95]
	s_add_u32 m0, s10, 0x6000
	v_mfma_f32_32x32x16_bf16 v[64:79], v[244:247], v[200:203], v[64:79]
	global_load_lds_dwordx4 v190, s[4:5]
	global_load_lds_dwordx4 v190, s[4:5] offset:1024
	v_mfma_f32_32x32x16_bf16 v[48:63], v[240:243], v[204:207], v[48:63]
	global_load_lds_dwordx4 v190, s[4:5] offset:2048
	global_load_lds_dwordx4 v190, s[4:5] offset:3072
	s_add_u32 m0, s11, 0xa000
	v_mfma_f32_32x32x16_bf16 v[32:47], v[244:247], v[204:207], v[32:47]
	global_load_lds_dwordx4 v191, s[6:7]
	global_load_lds_dwordx4 v191, s[6:7] offset:1024
	v_mfma_f32_32x32x16_bf16 v[16:31], v[240:243], v[208:211], v[16:31]
	s_add_u32 s4, s4, 0x202000
	s_addc_u32 s5, s5, 0
	v_mfma_f32_32x32x16_bf16 v[0:15], v[244:247], v[208:211], v[0:15]
	s_add_u32 s6, s6, 0x40000
	s_addc_u32 s7, s7, 0
	s_waitcnt lgkmcnt(0)
	ds_read_b128 v[240:243], v188 offset:49152
	ds_read_b128 v[244:247], v188 offset:51200
	v_mfma_f32_32x32x16_bf16 v[112:127], v[132:135], v[140:143], v[112:127]
	ds_read_b128 v[248:251], v131 offset:49152
	ds_read_b128 v[200:203], v131 offset:53248
	v_mfma_f32_32x32x16_bf16 v[96:111], v[136:139], v[140:143], v[96:111]
	ds_read_b128 v[204:207], v131 offset:57344
	ds_read_b128 v[208:211], v131 offset:61440
	v_mfma_f32_32x32x16_bf16 v[80:95], v[132:135], v[180:183], v[80:95]
	v_mfma_f32_32x32x16_bf16 v[64:79], v[136:139], v[180:183], v[64:79]
	v_mfma_f32_32x32x16_bf16 v[48:63], v[132:135], v[184:187], v[48:63]
	v_mfma_f32_32x32x16_bf16 v[32:47], v[136:139], v[184:187], v[32:47]
	v_mfma_f32_32x32x16_bf16 v[16:31], v[132:135], v[236:239], v[16:31]
	v_mfma_f32_32x32x16_bf16 v[0:15], v[136:139], v[236:239], v[0:15]
	s_waitcnt lgkmcnt(0)
	s_waitcnt vmcnt(6)
	s_barrier
	ds_read_b128 v[132:135], v156
	ds_read_b128 v[136:139], v156 offset:2048
	v_mfma_f32_32x32x16_bf16 v[112:127], v[240:243], v[248:251], v[112:127]
	ds_read_b128 v[140:143], v129
	ds_read_b128 v[180:183], v129 offset:4096
	v_mfma_f32_32x32x16_bf16 v[96:111], v[244:247], v[248:251], v[96:111]
	ds_read_b128 v[184:187], v129 offset:8192
	ds_read_b128 v[236:239], v129 offset:12288
	v_mfma_f32_32x32x16_bf16 v[80:95], v[240:243], v[200:203], v[80:95]
	v_mfma_f32_32x32x16_bf16 v[64:79], v[244:247], v[200:203], v[64:79]
	v_mfma_f32_32x32x16_bf16 v[48:63], v[240:243], v[204:207], v[48:63]
	v_mfma_f32_32x32x16_bf16 v[32:47], v[244:247], v[204:207], v[32:47]
	v_mfma_f32_32x32x16_bf16 v[16:31], v[240:243], v[208:211], v[16:31]
	v_mfma_f32_32x32x16_bf16 v[0:15], v[244:247], v[208:211], v[0:15]
	s_waitcnt lgkmcnt(0)
	ds_read_b128 v[240:243], v188
	ds_read_b128 v[244:247], v188 offset:2048
	v_mfma_f32_32x32x16_bf16 v[112:127], v[132:135], v[140:143], v[112:127]
	ds_read_b128 v[248:251], v131
	ds_read_b128 v[200:203], v131 offset:4096
	v_mfma_f32_32x32x16_bf16 v[96:111], v[136:139], v[140:143], v[96:111]
	ds_read_b128 v[204:207], v131 offset:8192
	ds_read_b128 v[208:211], v131 offset:12288
	v_mfma_f32_32x32x16_bf16 v[80:95], v[132:135], v[180:183], v[80:95]
	v_mfma_f32_32x32x16_bf16 v[64:79], v[136:139], v[180:183], v[64:79]
	v_mfma_f32_32x32x16_bf16 v[48:63], v[132:135], v[184:187], v[48:63]
	v_mfma_f32_32x32x16_bf16 v[32:47], v[136:139], v[184:187], v[32:47]
	v_mfma_f32_32x32x16_bf16 v[16:31], v[132:135], v[236:239], v[16:31]
	v_mfma_f32_32x32x16_bf16 v[0:15], v[136:139], v[236:239], v[0:15]
	s_waitcnt lgkmcnt(0)
	s_waitcnt vmcnt(0)
	s_barrier
	ds_read_b128 v[132:135], v156 offset:24576
	ds_read_b128 v[136:139], v156 offset:26624
	v_mfma_f32_32x32x16_bf16 v[112:127], v[240:243], v[248:251], v[112:127]
	ds_read_b128 v[140:143], v129 offset:24576
	ds_read_b128 v[180:183], v129 offset:28672
	v_mfma_f32_32x32x16_bf16 v[96:111], v[244:247], v[248:251], v[96:111]
	ds_read_b128 v[184:187], v129 offset:32768
	ds_read_b128 v[236:239], v129 offset:36864
	v_mfma_f32_32x32x16_bf16 v[80:95], v[240:243], v[200:203], v[80:95]
	v_mfma_f32_32x32x16_bf16 v[64:79], v[244:247], v[200:203], v[64:79]
	v_mfma_f32_32x32x16_bf16 v[48:63], v[240:243], v[204:207], v[48:63]
	v_mfma_f32_32x32x16_bf16 v[32:47], v[244:247], v[204:207], v[32:47]
	v_mfma_f32_32x32x16_bf16 v[16:31], v[240:243], v[208:211], v[16:31]
	v_mfma_f32_32x32x16_bf16 v[0:15], v[244:247], v[208:211], v[0:15]
	s_waitcnt lgkmcnt(0)
	ds_read_b128 v[240:243], v188 offset:24576
	ds_read_b128 v[244:247], v188 offset:26624
	v_mfma_f32_32x32x16_bf16 v[112:127], v[132:135], v[140:143], v[112:127]
	ds_read_b128 v[248:251], v131 offset:24576
	ds_read_b128 v[200:203], v131 offset:28672
	v_mfma_f32_32x32x16_bf16 v[96:111], v[136:139], v[140:143], v[96:111]
	ds_read_b128 v[204:207], v131 offset:32768
	ds_read_b128 v[208:211], v131 offset:36864
	v_mfma_f32_32x32x16_bf16 v[80:95], v[132:135], v[180:183], v[80:95]
	v_mfma_f32_32x32x16_bf16 v[64:79], v[136:139], v[180:183], v[64:79]
	v_mfma_f32_32x32x16_bf16 v[48:63], v[132:135], v[184:187], v[48:63]
	v_mfma_f32_32x32x16_bf16 v[32:47], v[136:139], v[184:187], v[32:47]
	v_mfma_f32_32x32x16_bf16 v[16:31], v[132:135], v[236:239], v[16:31]
	v_mfma_f32_32x32x16_bf16 v[0:15], v[136:139], v[236:239], v[0:15]
	s_waitcnt lgkmcnt(0)
	v_mfma_f32_32x32x16_bf16 v[112:127], v[240:243], v[248:251], v[112:127]
	v_mfma_f32_32x32x16_bf16 v[96:111], v[244:247], v[248:251], v[96:111]
	v_mfma_f32_32x32x16_bf16 v[80:95], v[240:243], v[200:203], v[80:95]
	v_mfma_f32_32x32x16_bf16 v[64:79], v[244:247], v[200:203], v[64:79]
	v_mfma_f32_32x32x16_bf16 v[48:63], v[240:243], v[204:207], v[48:63]
	v_mfma_f32_32x32x16_bf16 v[32:47], v[244:247], v[204:207], v[32:47]
	v_mfma_f32_32x32x16_bf16 v[16:31], v[240:243], v[208:211], v[16:31]
	v_mfma_f32_32x32x16_bf16 v[0:15], v[244:247], v[208:211], v[0:15]
	s_nop 15
	v_or_b32_e32 v190, 8, v150
	v_or_b32_e32 v191, 9, v150
	v_or_b32_e32 v192, 10, v150
	v_or_b32_e32 v193, 11, v150
	v_or_b32_e32 v194, 16, v150
	v_or_b32_e32 v195, 17, v150
	v_or_b32_e32 v200, 18, v150
	v_or_b32_e32 v201, 19, v150
	v_or_b32_e32 v202, 24, v150
	v_or_b32_e32 v203, 25, v150
	v_or_b32_e32 v204, 26, v150
	v_or_b32_e32 v205, 27, v150
	v_or_b32_e32 v206, 32, v150
	v_or_b32_e32 v207, 33, v150
	v_or_b32_e32 v208, 34, v150
	v_or_b32_e32 v209, 35, v150
	v_or_b32_e32 v210, 40, v150
	v_or_b32_e32 v211, 41, v150
	v_or_b32_e32 v212, 42, v150
	v_or_b32_e32 v213, 43, v150
	v_or_b32_e32 v214, 48, v150
	v_or_b32_e32 v215, 49, v150
	v_or_b32_e32 v216, 50, v150
	v_or_b32_e32 v217, 51, v150
	v_or_b32_e32 v218, 56, v150
	v_or_b32_e32 v219, 57, v150
	v_or_b32_e32 v220, 58, v150
	v_or_b32_e32 v221, 59, v150

.LBB0_887:
	s_or_saveexec_b64 s[0:1], s[0:1]
	v_mov_b32_e32 v127, 0
	v_mov_b32_e32 v126, 0
	v_mov_b32_e32 v125, 0
	v_mov_b32_e32 v124, 0
	v_mov_b32_e32 v123, 0
	v_mov_b32_e32 v122, 0
	v_mov_b32_e32 v121, 0
	v_mov_b32_e32 v120, 0
	v_mov_b32_e32 v119, 0
	v_mov_b32_e32 v118, 0
	v_mov_b32_e32 v117, 0
	v_mov_b32_e32 v116, 0
	v_mov_b32_e32 v115, 0
	v_mov_b32_e32 v114, 0
	v_mov_b32_e32 v113, 0
	v_mov_b32_e32 v112, 0
	v_mov_b32_e32 v63, 0
	v_mov_b32_e32 v62, 0
	v_mov_b32_e32 v61, 0
	v_mov_b32_e32 v60, 0
	v_mov_b32_e32 v59, 0
	v_mov_b32_e32 v58, 0
	v_mov_b32_e32 v57, 0
	v_mov_b32_e32 v56, 0
	v_mov_b32_e32 v55, 0
	v_mov_b32_e32 v54, 0
	v_mov_b32_e32 v53, 0
	v_mov_b32_e32 v52, 0
	v_mov_b32_e32 v51, 0
	v_mov_b32_e32 v50, 0
	v_mov_b32_e32 v49, 0
	v_mov_b32_e32 v48, 0
	v_mov_b32_e32 v111, 0
	v_mov_b32_e32 v110, 0
	v_mov_b32_e32 v109, 0
	v_mov_b32_e32 v108, 0
	v_mov_b32_e32 v107, 0
	v_mov_b32_e32 v106, 0
	v_mov_b32_e32 v105, 0
	v_mov_b32_e32 v104, 0
	v_mov_b32_e32 v103, 0
	v_mov_b32_e32 v102, 0
	v_mov_b32_e32 v101, 0
	v_mov_b32_e32 v100, 0
	v_mov_b32_e32 v99, 0
	v_mov_b32_e32 v98, 0
	v_mov_b32_e32 v97, 0
	v_mov_b32_e32 v96, 0
	v_mov_b32_e32 v47, 0
	v_mov_b32_e32 v46, 0
	v_mov_b32_e32 v45, 0
	v_mov_b32_e32 v44, 0
	v_mov_b32_e32 v43, 0
	v_mov_b32_e32 v42, 0
	v_mov_b32_e32 v41, 0
	v_mov_b32_e32 v40, 0
	v_mov_b32_e32 v39, 0
	v_mov_b32_e32 v38, 0
	v_mov_b32_e32 v37, 0
	v_mov_b32_e32 v36, 0
	v_mov_b32_e32 v35, 0
	v_mov_b32_e32 v34, 0
	v_mov_b32_e32 v33, 0
	v_mov_b32_e32 v32, 0
	s_xor_b64 exec, exec, s[0:1]
	s_cbranch_execz .LBB0_891
	v_readfirstlane_b32 s78, v148
	v_readfirstlane_b32 s79, v150
	v_readfirstlane_b32 s76, v178
	v_mbcnt_lo_u32_b32 v164, -1, 0
	v_mbcnt_hi_u32_b32 v164, -1, v164
	s_nop 3
	s_lshl_b32 s78, s78, 14
	s_lshl_b32 s79, s79, 13
	s_add_u32 s72, s90, s78
	s_addc_u32 s73, s91, 0
	s_add_u32 s74, s90, s79
	s_addc_u32 s75, s91, 0
	s_add_u32 s74, s74, 0x1bbc8000
	s_addc_u32 s75, s75, 0
	v_and_b32_e32 v165, 31, v164
	v_lshrrev_b32_e32 v166, 5, v164
	v_bfe_u32 v167, v164, 2, 2
	v_xor_b32_e32 v166, v166, v167
	v_lshlrev_b32_e32 v166, 4, v166
	v_lshl_or_b32 v165, v165, 6, v166
	v_lshrrev_b32_e32 v167, 10, v178
	v_lshrrev_b32_e32 v166, 1, v167
	v_lshl_or_b32 v156, v166, 11, v165
	v_and_b32_e32 v166, 1, v167
	v_lshl_or_b32 v158, v166, 12, v165
	v_or_b32_e32 v158, 0x4000, v158
	v_xor_b32_e32 v157, 32, v156
	v_xor_b32_e32 v159, 32, v158
	v_lshrrev_b32_e32 v165, 2, v164
	v_lshrrev_b32_e32 v166, 4, v164
	v_xor_b32_e32 v166, v166, v164
	v_and_b32_e32 v166, 3, v166
	v_lshlrev_b32_e32 v166, 4, v166
	v_lshl_or_b32 v165, v165, 6, v166
	v_or_b32_e32 v160, v165, v178
	v_add_u32_e32 v161, 0x1000, v160
	v_add_u32_e32 v162, 0x2000, v160
	v_add_u32_e32 v163, 0x3000, v160
	s_add_u32 m0, s76, 0x2000
	s_nop 0
	global_load_lds_dwordx4 v162, s[72:73]
	s_add_u32 m0, s76, 0x3000
	s_nop 0
	global_load_lds_dwordx4 v163, s[72:73]
	s_add_u32 m0, s76, 0x4000
	s_nop 0
	global_load_lds_dwordx4 v160, s[74:75]
	s_add_u32 m0, s76, 0x5000
	s_nop 0
	global_load_lds_dwordx4 v161, s[74:75]
	s_add_u32 s72, s72, 0x202000
	s_addc_u32 s73, s73, 0
	s_add_u32 s74, s74, 0x10000
	s_addc_u32 s75, s75, 0
	s_lshl_b32 s78, s76, 2
	s_lshl_b32 s79, s76, 1
	v_sub_u32_e32 v162, v160, v178
	v_lshl_add_u32 v163, v178, 1, v162
	v_lshl_add_u32 v162, v178, 2, v162
	s_add_u32 m0, s78, 0x6000
	s_nop 0
	global_load_lds_dwordx4 v162, s[72:73]
	global_load_lds_dwordx4 v162, s[72:73] offset:1024
	global_load_lds_dwordx4 v162, s[72:73] offset:2048
	global_load_lds_dwordx4 v162, s[72:73] offset:3072
	s_add_u32 m0, s79, 0xa000
	s_nop 0
	global_load_lds_dwordx4 v163, s[74:75]
	global_load_lds_dwordx4 v163, s[74:75] offset:1024
	s_add_u32 s72, s72, 0x202000
	s_addc_u32 s73, s73, 0
	s_add_u32 s74, s74, 0x10000
	s_addc_u32 s75, s75, 0
	s_add_u32 m0, s78, 0xc000
	s_nop 0
	global_load_lds_dwordx4 v162, s[72:73]
	global_load_lds_dwordx4 v162, s[72:73] offset:1024
	global_load_lds_dwordx4 v162, s[72:73] offset:2048
	global_load_lds_dwordx4 v162, s[72:73] offset:3072
	s_add_u32 m0, s79, 0x10000
	s_nop 0
	global_load_lds_dwordx4 v163, s[74:75]
	global_load_lds_dwordx4 v163, s[74:75] offset:1024
	s_add_u32 s72, s72, 0x202000
	s_addc_u32 s73, s73, 0
	s_add_u32 s74, s74, 0x10000
	s_addc_u32 s75, s75, 0
	s_waitcnt vmcnt(12)
	s_barrier
	ds_read_b128 v[200:203], v158
	ds_read_b128 v[204:207], v158 offset:2048
	ds_read_b128 v[208:211], v156
	ds_read_b128 v[212:215], v156 offset:4096
	ds_read_b128 v[216:219], v156 offset:8192
	ds_read_b128 v[220:223], v156 offset:12288
	s_waitcnt lgkmcnt(0)
	ds_read_b128 v[224:227], v159
	ds_read_b128 v[228:231], v159 offset:2048
	v_mfma_f32_32x32x16_bf16 v[80:95], v[200:203], v[208:211], 0
	ds_read_b128 v[232:235], v157
	ds_read_b128 v[236:239], v157 offset:4096
	v_mfma_f32_32x32x16_bf16 v[64:79], v[204:207], v[208:211], 0
	ds_read_b128 v[240:243], v157 offset:8192
	ds_read_b128 v[152:155], v157 offset:12288
	v_mfma_f32_32x32x16_bf16 v[16:31], v[200:203], v[212:215], 0
	v_mfma_f32_32x32x16_bf16 v[0:15], v[204:207], v[212:215], 0
	v_mfma_f32_32x32x16_bf16 v[112:127], v[200:203], v[216:219], 0
	v_mfma_f32_32x32x16_bf16 v[96:111], v[204:207], v[216:219], 0
	v_mfma_f32_32x32x16_bf16 v[48:63], v[200:203], v[220:223], 0
	v_mfma_f32_32x32x16_bf16 v[32:47], v[204:207], v[220:223], 0
	s_waitcnt lgkmcnt(0)
	s_waitcnt vmcnt(6)
	s_barrier
	ds_read_b128 v[200:203], v158 offset:24576
	ds_read_b128 v[204:207], v158 offset:26624
	v_mfma_f32_32x32x16_bf16 v[80:95], v[224:227], v[232:235], v[80:95]
	ds_read_b128 v[208:211], v156 offset:24576
	ds_read_b128 v[212:215], v156 offset:28672
	v_mfma_f32_32x32x16_bf16 v[64:79], v[228:231], v[232:235], v[64:79]
	ds_read_b128 v[216:219], v156 offset:32768
	ds_read_b128 v[220:223], v156 offset:36864
	v_mfma_f32_32x32x16_bf16 v[16:31], v[224:227], v[236:239], v[16:31]
	s_add_u32 m0, s78, 0x0
	v_mfma_f32_32x32x16_bf16 v[0:15], v[228:231], v[236:239], v[0:15]
	global_load_lds_dwordx4 v162, s[72:73]
	global_load_lds_dwordx4 v162, s[72:73] offset:1024
	v_mfma_f32_32x32x16_bf16 v[112:127], v[224:227], v[240:243], v[112:127]
	global_load_lds_dwordx4 v162, s[72:73] offset:2048
	global_load_lds_dwordx4 v162, s[72:73] offset:3072
	s_add_u32 m0, s79, 0x4000
	v_mfma_f32_32x32x16_bf16 v[96:111], v[228:231], v[240:243], v[96:111]
	global_load_lds_dwordx4 v163, s[74:75]
	global_load_lds_dwordx4 v163, s[74:75] offset:1024
	v_mfma_f32_32x32x16_bf16 v[48:63], v[224:227], v[152:155], v[48:63]
	s_add_u32 s72, s72, 0x202000
	s_addc_u32 s73, s73, 0
	v_mfma_f32_32x32x16_bf16 v[32:47], v[228:231], v[152:155], v[32:47]
	s_add_u32 s74, s74, 0x10000
	s_addc_u32 s75, s75, 0
	s_waitcnt lgkmcnt(0)
	ds_read_b128 v[224:227], v159 offset:24576
	ds_read_b128 v[228:231], v159 offset:26624
	v_mfma_f32_32x32x16_bf16 v[80:95], v[200:203], v[208:211], v[80:95]
	ds_read_b128 v[232:235], v157 offset:24576
	ds_read_b128 v[236:239], v157 offset:28672
	v_mfma_f32_32x32x16_bf16 v[64:79], v[204:207], v[208:211], v[64:79]
	ds_read_b128 v[240:243], v157 offset:32768
	ds_read_b128 v[152:155], v157 offset:36864
	v_mfma_f32_32x32x16_bf16 v[16:31], v[200:203], v[212:215], v[16:31]
	v_mfma_f32_32x32x16_bf16 v[0:15], v[204:207], v[212:215], v[0:15]
	v_mfma_f32_32x32x16_bf16 v[112:127], v[200:203], v[216:219], v[112:127]
	v_mfma_f32_32x32x16_bf16 v[96:111], v[204:207], v[216:219], v[96:111]
	v_mfma_f32_32x32x16_bf16 v[48:63], v[200:203], v[220:223], v[48:63]
	v_mfma_f32_32x32x16_bf16 v[32:47], v[204:207], v[220:223], v[32:47]
	s_waitcnt lgkmcnt(0)
	s_waitcnt vmcnt(6)
	s_barrier
	ds_read_b128 v[200:203], v158 offset:49152
	ds_read_b128 v[204:207], v158 offset:51200
	v_mfma_f32_32x32x16_bf16 v[80:95], v[224:227], v[232:235], v[80:95]
	ds_read_b128 v[208:211], v156 offset:49152
	ds_read_b128 v[212:215], v156 offset:53248
	v_mfma_f32_32x32x16_bf16 v[64:79], v[228:231], v[232:235], v[64:79]
	ds_read_b128 v[216:219], v156 offset:57344
	ds_read_b128 v[220:223], v156 offset:61440
	v_mfma_f32_32x32x16_bf16 v[16:31], v[224:227], v[236:239], v[16:31]
	s_add_u32 m0, s78, 0x6000
	v_mfma_f32_32x32x16_bf16 v[0:15], v[228:231], v[236:239], v[0:15]
	global_load_lds_dwordx4 v162, s[72:73]
	global_load_lds_dwordx4 v162, s[72:73] offset:1024
	v_mfma_f32_32x32x16_bf16 v[112:127], v[224:227], v[240:243], v[112:127]
	global_load_lds_dwordx4 v162, s[72:73] offset:2048
	global_load_lds_dwordx4 v162, s[72:73] offset:3072
	s_add_u32 m0, s79, 0xa000
	v_mfma_f32_32x32x16_bf16 v[96:111], v[228:231], v[240:243], v[96:111]
	global_load_lds_dwordx4 v163, s[74:75]
	global_load_lds_dwordx4 v163, s[74:75] offset:1024
	v_mfma_f32_32x32x16_bf16 v[48:63], v[224:227], v[152:155], v[48:63]
	s_add_u32 s72, s72, 0x202000
	s_addc_u32 s73, s73, 0
	v_mfma_f32_32x32x16_bf16 v[32:47], v[228:231], v[152:155], v[32:47]
	s_add_u32 s74, s74, 0x10000
	s_addc_u32 s75, s75, 0
	s_waitcnt lgkmcnt(0)
	ds_read_b128 v[224:227], v159 offset:49152
	ds_read_b128 v[228:231], v159 offset:51200
	v_mfma_f32_32x32x16_bf16 v[80:95], v[200:203], v[208:211], v[80:95]
	ds_read_b128 v[232:235], v157 offset:49152
	ds_read_b128 v[236:239], v157 offset:53248
	v_mfma_f32_32x32x16_bf16 v[64:79], v[204:207], v[208:211], v[64:79]
	ds_read_b128 v[240:243], v157 offset:57344
	ds_read_b128 v[152:155], v157 offset:61440
	v_mfma_f32_32x32x16_bf16 v[16:31], v[200:203], v[212:215], v[16:31]
	v_mfma_f32_32x32x16_bf16 v[0:15], v[204:207], v[212:215], v[0:15]
	v_mfma_f32_32x32x16_bf16 v[112:127], v[200:203], v[216:219], v[112:127]
	v_mfma_f32_32x32x16_bf16 v[96:111], v[204:207], v[216:219], v[96:111]
	v_mfma_f32_32x32x16_bf16 v[48:63], v[200:203], v[220:223], v[48:63]
	v_mfma_f32_32x32x16_bf16 v[32:47], v[204:207], v[220:223], v[32:47]
	s_waitcnt lgkmcnt(0)
	s_waitcnt vmcnt(6)
	s_barrier
	ds_read_b128 v[200:203], v158
	ds_read_b128 v[204:207], v158 offset:2048
	v_mfma_f32_32x32x16_bf16 v[80:95], v[224:227], v[232:235], v[80:95]
	ds_read_b128 v[208:211], v156
	ds_read_b128 v[212:215], v156 offset:4096
	v_mfma_f32_32x32x16_bf16 v[64:79], v[228:231], v[232:235], v[64:79]
	ds_read_b128 v[216:219], v156 offset:8192
	ds_read_b128 v[220:223], v156 offset:12288
	v_mfma_f32_32x32x16_bf16 v[16:31], v[224:227], v[236:239], v[16:31]
	s_add_u32 m0, s78, 0xc000
	v_mfma_f32_32x32x16_bf16 v[0:15], v[228:231], v[236:239], v[0:15]
	global_load_lds_dwordx4 v162, s[72:73]
	global_load_lds_dwordx4 v162, s[72:73] offset:1024
	v_mfma_f32_32x32x16_bf16 v[112:127], v[224:227], v[240:243], v[112:127]
	global_load_lds_dwordx4 v162, s[72:73] offset:2048
	global_load_lds_dwordx4 v162, s[72:73] offset:3072
	s_add_u32 m0, s79, 0x10000
	v_mfma_f32_32x32x16_bf16 v[96:111], v[228:231], v[240:243], v[96:111]
	global_load_lds_dwordx4 v163, s[74:75]
	global_load_lds_dwordx4 v163, s[74:75] offset:1024
	v_mfma_f32_32x32x16_bf16 v[48:63], v[224:227], v[152:155], v[48:63]
	s_add_u32 s72, s72, 0x202000
	s_addc_u32 s73, s73, 0
	v_mfma_f32_32x32x16_bf16 v[32:47], v[228:231], v[152:155], v[32:47]
	s_add_u32 s74, s74, 0x10000
	s_addc_u32 s75, s75, 0
	s_waitcnt lgkmcnt(0)
	s_mov_b32 s77, 8
.Lgemm_p6_loop:
	ds_read_b128 v[224:227], v159
	ds_read_b128 v[228:231], v159 offset:2048
	v_mfma_f32_32x32x16_bf16 v[80:95], v[200:203], v[208:211], v[80:95]
	ds_read_b128 v[232:235], v157
	ds_read_b128 v[236:239], v157 offset:4096
	v_mfma_f32_32x32x16_bf16 v[64:79], v[204:207], v[208:211], v[64:79]
	ds_read_b128 v[240:243], v157 offset:8192
	ds_read_b128 v[152:155], v157 offset:12288
	v_mfma_f32_32x32x16_bf16 v[16:31], v[200:203], v[212:215], v[16:31]
	v_mfma_f32_32x32x16_bf16 v[0:15], v[204:207], v[212:215], v[0:15]
	v_mfma_f32_32x32x16_bf16 v[112:127], v[200:203], v[216:219], v[112:127]
	v_mfma_f32_32x32x16_bf16 v[96:111], v[204:207], v[216:219], v[96:111]
	v_mfma_f32_32x32x16_bf16 v[48:63], v[200:203], v[220:223], v[48:63]
	v_mfma_f32_32x32x16_bf16 v[32:47], v[204:207], v[220:223], v[32:47]
	s_waitcnt lgkmcnt(0)
	s_waitcnt vmcnt(6)
	s_barrier
	ds_read_b128 v[200:203], v158 offset:24576
	ds_read_b128 v[204:207], v158 offset:26624
	v_mfma_f32_32x32x16_bf16 v[80:95], v[224:227], v[232:235], v[80:95]
	ds_read_b128 v[208:211], v156 offset:24576
	ds_read_b128 v[212:215], v156 offset:28672
	v_mfma_f32_32x32x16_bf16 v[64:79], v[228:231], v[232:235], v[64:79]
	ds_read_b128 v[216:219], v156 offset:32768
	ds_read_b128 v[220:223], v156 offset:36864
	v_mfma_f32_32x32x16_bf16 v[16:31], v[224:227], v[236:239], v[16:31]
	s_add_u32 m0, s78, 0x0
	v_mfma_f32_32x32x16_bf16 v[0:15], v[228:231], v[236:239], v[0:15]
	global_load_lds_dwordx4 v162, s[72:73]
	global_load_lds_dwordx4 v162, s[72:73] offset:1024
	v_mfma_f32_32x32x16_bf16 v[112:127], v[224:227], v[240:243], v[112:127]
	global_load_lds_dwordx4 v162, s[72:73] offset:2048
	global_load_lds_dwordx4 v162, s[72:73] offset:3072
	s_add_u32 m0, s79, 0x4000
	v_mfma_f32_32x32x16_bf16 v[96:111], v[228:231], v[240:243], v[96:111]
	global_load_lds_dwordx4 v163, s[74:75]
	global_load_lds_dwordx4 v163, s[74:75] offset:1024
	v_mfma_f32_32x32x16_bf16 v[48:63], v[224:227], v[152:155], v[48:63]
	s_add_u32 s72, s72, 0x202000
	s_addc_u32 s73, s73, 0
	v_mfma_f32_32x32x16_bf16 v[32:47], v[228:231], v[152:155], v[32:47]
	s_add_u32 s74, s74, 0x10000
	s_addc_u32 s75, s75, 0
	s_waitcnt lgkmcnt(0)
	ds_read_b128 v[224:227], v159 offset:24576
	ds_read_b128 v[228:231], v159 offset:26624
	v_mfma_f32_32x32x16_bf16 v[80:95], v[200:203], v[208:211], v[80:95]
	ds_read_b128 v[232:235], v157 offset:24576
	ds_read_b128 v[236:239], v157 offset:28672
	v_mfma_f32_32x32x16_bf16 v[64:79], v[204:207], v[208:211], v[64:79]
	ds_read_b128 v[240:243], v157 offset:32768
	ds_read_b128 v[152:155], v157 offset:36864
	v_mfma_f32_32x32x16_bf16 v[16:31], v[200:203], v[212:215], v[16:31]
	v_mfma_f32_32x32x16_bf16 v[0:15], v[204:207], v[212:215], v[0:15]
	v_mfma_f32_32x32x16_bf16 v[112:127], v[200:203], v[216:219], v[112:127]
	v_mfma_f32_32x32x16_bf16 v[96:111], v[204:207], v[216:219], v[96:111]
	v_mfma_f32_32x32x16_bf16 v[48:63], v[200:203], v[220:223], v[48:63]
	v_mfma_f32_32x32x16_bf16 v[32:47], v[204:207], v[220:223], v[32:47]
	s_waitcnt lgkmcnt(0)
	s_waitcnt vmcnt(6)
	s_barrier
	ds_read_b128 v[200:203], v158 offset:49152
	ds_read_b128 v[204:207], v158 offset:51200
	v_mfma_f32_32x32x16_bf16 v[80:95], v[224:227], v[232:235], v[80:95]
	ds_read_b128 v[208:211], v156 offset:49152
	ds_read_b128 v[212:215], v156 offset:53248
	v_mfma_f32_32x32x16_bf16 v[64:79], v[228:231], v[232:235], v[64:79]
	ds_read_b128 v[216:219], v156 offset:57344
	ds_read_b128 v[220:223], v156 offset:61440
	v_mfma_f32_32x32x16_bf16 v[16:31], v[224:227], v[236:239], v[16:31]
	s_add_u32 m0, s78, 0x6000
	v_mfma_f32_32x32x16_bf16 v[0:15], v[228:231], v[236:239], v[0:15]
	global_load_lds_dwordx4 v162, s[72:73]
	global_load_lds_dwordx4 v162, s[72:73] offset:1024
	v_mfma_f32_32x32x16_bf16 v[112:127], v[224:227], v[240:243], v[112:127]
	global_load_lds_dwordx4 v162, s[72:73] offset:2048
	global_load_lds_dwordx4 v162, s[72:73] offset:3072
	s_add_u32 m0, s79, 0xa000
	v_mfma_f32_32x32x16_bf16 v[96:111], v[228:231], v[240:243], v[96:111]
	global_load_lds_dwordx4 v163, s[74:75]
	global_load_lds_dwordx4 v163, s[74:75] offset:1024
	v_mfma_f32_32x32x16_bf16 v[48:63], v[224:227], v[152:155], v[48:63]
	s_add_u32 s72, s72, 0x202000
	s_addc_u32 s73, s73, 0
	v_mfma_f32_32x32x16_bf16 v[32:47], v[228:231], v[152:155], v[32:47]
	s_add_u32 s74, s74, 0x10000
	s_addc_u32 s75, s75, 0
	s_waitcnt lgkmcnt(0)
	ds_read_b128 v[224:227], v159 offset:49152
	ds_read_b128 v[228:231], v159 offset:51200
	v_mfma_f32_32x32x16_bf16 v[80:95], v[200:203], v[208:211], v[80:95]
	ds_read_b128 v[232:235], v157 offset:49152
	ds_read_b128 v[236:239], v157 offset:53248
	v_mfma_f32_32x32x16_bf16 v[64:79], v[204:207], v[208:211], v[64:79]
	ds_read_b128 v[240:243], v157 offset:57344
	ds_read_b128 v[152:155], v157 offset:61440
	v_mfma_f32_32x32x16_bf16 v[16:31], v[200:203], v[212:215], v[16:31]
	v_mfma_f32_32x32x16_bf16 v[0:15], v[204:207], v[212:215], v[0:15]
	v_mfma_f32_32x32x16_bf16 v[112:127], v[200:203], v[216:219], v[112:127]
	v_mfma_f32_32x32x16_bf16 v[96:111], v[204:207], v[216:219], v[96:111]
	v_mfma_f32_32x32x16_bf16 v[48:63], v[200:203], v[220:223], v[48:63]
	v_mfma_f32_32x32x16_bf16 v[32:47], v[204:207], v[220:223], v[32:47]
	s_waitcnt lgkmcnt(0)
	s_waitcnt vmcnt(6)
	s_barrier
	ds_read_b128 v[200:203], v158
	ds_read_b128 v[204:207], v158 offset:2048
	v_mfma_f32_32x32x16_bf16 v[80:95], v[224:227], v[232:235], v[80:95]
	ds_read_b128 v[208:211], v156
	ds_read_b128 v[212:215], v156 offset:4096
	v_mfma_f32_32x32x16_bf16 v[64:79], v[228:231], v[232:235], v[64:79]
	ds_read_b128 v[216:219], v156 offset:8192
	ds_read_b128 v[220:223], v156 offset:12288
	v_mfma_f32_32x32x16_bf16 v[16:31], v[224:227], v[236:239], v[16:31]
	s_add_u32 m0, s78, 0xc000
	v_mfma_f32_32x32x16_bf16 v[0:15], v[228:231], v[236:239], v[0:15]
	global_load_lds_dwordx4 v162, s[72:73]
	global_load_lds_dwordx4 v162, s[72:73] offset:1024
	v_mfma_f32_32x32x16_bf16 v[112:127], v[224:227], v[240:243], v[112:127]
	global_load_lds_dwordx4 v162, s[72:73] offset:2048
	global_load_lds_dwordx4 v162, s[72:73] offset:3072
	s_add_u32 m0, s79, 0x10000
	v_mfma_f32_32x32x16_bf16 v[96:111], v[228:231], v[240:243], v[96:111]
	global_load_lds_dwordx4 v163, s[74:75]
	global_load_lds_dwordx4 v163, s[74:75] offset:1024
	v_mfma_f32_32x32x16_bf16 v[48:63], v[224:227], v[152:155], v[48:63]
	s_add_u32 s72, s72, 0x202000
	s_addc_u32 s73, s73, 0
	v_mfma_f32_32x32x16_bf16 v[32:47], v[228:231], v[152:155], v[32:47]
	s_add_u32 s74, s74, 0x10000
	s_addc_u32 s75, s75, 0
	s_waitcnt lgkmcnt(0)
	s_sub_i32 s77, s77, 1
	s_cmp_lg_u32 s77, 0
	s_cbranch_scc1 .Lgemm_p6_loop
	ds_read_b128 v[224:227], v159
	ds_read_b128 v[228:231], v159 offset:2048
	v_mfma_f32_32x32x16_bf16 v[80:95], v[200:203], v[208:211], v[80:95]
	ds_read_b128 v[232:235], v157
	ds_read_b128 v[236:239], v157 offset:4096
	v_mfma_f32_32x32x16_bf16 v[64:79], v[204:207], v[208:211], v[64:79]
	ds_read_b128 v[240:243], v157 offset:8192
	ds_read_b128 v[152:155], v157 offset:12288
	v_mfma_f32_32x32x16_bf16 v[16:31], v[200:203], v[212:215], v[16:31]
	v_mfma_f32_32x32x16_bf16 v[0:15], v[204:207], v[212:215], v[0:15]
	v_mfma_f32_32x32x16_bf16 v[112:127], v[200:203], v[216:219], v[112:127]
	v_mfma_f32_32x32x16_bf16 v[96:111], v[204:207], v[216:219], v[96:111]
	v_mfma_f32_32x32x16_bf16 v[48:63], v[200:203], v[220:223], v[48:63]
	v_mfma_f32_32x32x16_bf16 v[32:47], v[204:207], v[220:223], v[32:47]
	s_waitcnt lgkmcnt(0)
	s_waitcnt vmcnt(6)
	s_barrier
	ds_read_b128 v[200:203], v158 offset:24576
	ds_read_b128 v[204:207], v158 offset:26624
	v_mfma_f32_32x32x16_bf16 v[80:95], v[224:227], v[232:235], v[80:95]
	ds_read_b128 v[208:211], v156 offset:24576
	ds_read_b128 v[212:215], v156 offset:28672
	v_mfma_f32_32x32x16_bf16 v[64:79], v[228:231], v[232:235], v[64:79]
	ds_read_b128 v[216:219], v156 offset:32768
	ds_read_b128 v[220:223], v156 offset:36864
	v_mfma_f32_32x32x16_bf16 v[16:31], v[224:227], v[236:239], v[16:31]
	s_add_u32 m0, s78, 0x0
	v_mfma_f32_32x32x16_bf16 v[0:15], v[228:231], v[236:239], v[0:15]
	global_load_lds_dwordx4 v162, s[72:73]
	global_load_lds_dwordx4 v162, s[72:73] offset:1024
	v_mfma_f32_32x32x16_bf16 v[112:127], v[224:227], v[240:243], v[112:127]
	global_load_lds_dwordx4 v162, s[72:73] offset:2048
	global_load_lds_dwordx4 v162, s[72:73] offset:3072
	s_add_u32 m0, s79, 0x4000
	v_mfma_f32_32x32x16_bf16 v[96:111], v[228:231], v[240:243], v[96:111]
	global_load_lds_dwordx4 v163, s[74:75]
	global_load_lds_dwordx4 v163, s[74:75] offset:1024
	v_mfma_f32_32x32x16_bf16 v[48:63], v[224:227], v[152:155], v[48:63]
	s_add_u32 s72, s72, 0x202000
	s_addc_u32 s73, s73, 0
	v_mfma_f32_32x32x16_bf16 v[32:47], v[228:231], v[152:155], v[32:47]
	s_add_u32 s74, s74, 0x10000
	s_addc_u32 s75, s75, 0
	s_waitcnt lgkmcnt(0)
	ds_read_b128 v[224:227], v159 offset:24576
	ds_read_b128 v[228:231], v159 offset:26624
	v_mfma_f32_32x32x16_bf16 v[80:95], v[200:203], v[208:211], v[80:95]
	ds_read_b128 v[232:235], v157 offset:24576
	ds_read_b128 v[236:239], v157 offset:28672
	v_mfma_f32_32x32x16_bf16 v[64:79], v[204:207], v[208:211], v[64:79]
	ds_read_b128 v[240:243], v157 offset:32768
	ds_read_b128 v[152:155], v157 offset:36864
	v_mfma_f32_32x32x16_bf16 v[16:31], v[200:203], v[212:215], v[16:31]
	v_mfma_f32_32x32x16_bf16 v[0:15], v[204:207], v[212:215], v[0:15]
	v_mfma_f32_32x32x16_bf16 v[112:127], v[200:203], v[216:219], v[112:127]
	v_mfma_f32_32x32x16_bf16 v[96:111], v[204:207], v[216:219], v[96:111]
	v_mfma_f32_32x32x16_bf16 v[48:63], v[200:203], v[220:223], v[48:63]
	v_mfma_f32_32x32x16_bf16 v[32:47], v[204:207], v[220:223], v[32:47]
	s_waitcnt lgkmcnt(0)
	s_waitcnt vmcnt(6)
	s_barrier
	ds_read_b128 v[200:203], v158 offset:49152
	ds_read_b128 v[204:207], v158 offset:51200
	v_mfma_f32_32x32x16_bf16 v[80:95], v[224:227], v[232:235], v[80:95]
	ds_read_b128 v[208:211], v156 offset:49152
	ds_read_b128 v[212:215], v156 offset:53248
	v_mfma_f32_32x32x16_bf16 v[64:79], v[228:231], v[232:235], v[64:79]
	ds_read_b128 v[216:219], v156 offset:57344
	ds_read_b128 v[220:223], v156 offset:61440
	v_mfma_f32_32x32x16_bf16 v[16:31], v[224:227], v[236:239], v[16:31]
	s_add_u32 m0, s78, 0x6000
	v_mfma_f32_32x32x16_bf16 v[0:15], v[228:231], v[236:239], v[0:15]
	global_load_lds_dwordx4 v162, s[72:73]
	global_load_lds_dwordx4 v162, s[72:73] offset:1024
	v_mfma_f32_32x32x16_bf16 v[112:127], v[224:227], v[240:243], v[112:127]
	global_load_lds_dwordx4 v162, s[72:73] offset:2048
	global_load_lds_dwordx4 v162, s[72:73] offset:3072
	s_add_u32 m0, s79, 0xa000
	v_mfma_f32_32x32x16_bf16 v[96:111], v[228:231], v[240:243], v[96:111]
	global_load_lds_dwordx4 v163, s[74:75]
	global_load_lds_dwordx4 v163, s[74:75] offset:1024
	v_mfma_f32_32x32x16_bf16 v[48:63], v[224:227], v[152:155], v[48:63]
	s_add_u32 s72, s72, 0x202000
	s_addc_u32 s73, s73, 0
	v_mfma_f32_32x32x16_bf16 v[32:47], v[228:231], v[152:155], v[32:47]
	s_add_u32 s74, s74, 0x10000
	s_addc_u32 s75, s75, 0
	s_waitcnt lgkmcnt(0)
	ds_read_b128 v[224:227], v159 offset:49152
	ds_read_b128 v[228:231], v159 offset:51200
	v_mfma_f32_32x32x16_bf16 v[80:95], v[200:203], v[208:211], v[80:95]
	ds_read_b128 v[232:235], v157 offset:49152
	ds_read_b128 v[236:239], v157 offset:53248
	v_mfma_f32_32x32x16_bf16 v[64:79], v[204:207], v[208:211], v[64:79]
	ds_read_b128 v[240:243], v157 offset:57344
	ds_read_b128 v[152:155], v157 offset:61440
	v_mfma_f32_32x32x16_bf16 v[16:31], v[200:203], v[212:215], v[16:31]
	v_mfma_f32_32x32x16_bf16 v[0:15], v[204:207], v[212:215], v[0:15]
	v_mfma_f32_32x32x16_bf16 v[112:127], v[200:203], v[216:219], v[112:127]
	v_mfma_f32_32x32x16_bf16 v[96:111], v[204:207], v[216:219], v[96:111]
	v_mfma_f32_32x32x16_bf16 v[48:63], v[200:203], v[220:223], v[48:63]
	v_mfma_f32_32x32x16_bf16 v[32:47], v[204:207], v[220:223], v[32:47]
	s_waitcnt lgkmcnt(0)
	s_waitcnt vmcnt(6)
	s_barrier
	ds_read_b128 v[200:203], v158
	ds_read_b128 v[204:207], v158 offset:2048
	v_mfma_f32_32x32x16_bf16 v[80:95], v[224:227], v[232:235], v[80:95]
	ds_read_b128 v[208:211], v156
	ds_read_b128 v[212:215], v156 offset:4096
	v_mfma_f32_32x32x16_bf16 v[64:79], v[228:231], v[232:235], v[64:79]
	ds_read_b128 v[216:219], v156 offset:8192
	ds_read_b128 v[220:223], v156 offset:12288
	v_mfma_f32_32x32x16_bf16 v[16:31], v[224:227], v[236:239], v[16:31]
	v_mfma_f32_32x32x16_bf16 v[0:15], v[228:231], v[236:239], v[0:15]
	v_mfma_f32_32x32x16_bf16 v[112:127], v[224:227], v[240:243], v[112:127]
	v_mfma_f32_32x32x16_bf16 v[96:111], v[228:231], v[240:243], v[96:111]
	v_mfma_f32_32x32x16_bf16 v[48:63], v[224:227], v[152:155], v[48:63]
	v_mfma_f32_32x32x16_bf16 v[32:47], v[228:231], v[152:155], v[32:47]
	s_waitcnt lgkmcnt(0)
	ds_read_b128 v[224:227], v159
	ds_read_b128 v[228:231], v159 offset:2048
	v_mfma_f32_32x32x16_bf16 v[80:95], v[200:203], v[208:211], v[80:95]
	ds_read_b128 v[232:235], v157
	ds_read_b128 v[236:239], v157 offset:4096
	v_mfma_f32_32x32x16_bf16 v[64:79], v[204:207], v[208:211], v[64:79]
	ds_read_b128 v[240:243], v157 offset:8192
	ds_read_b128 v[152:155], v157 offset:12288
	v_mfma_f32_32x32x16_bf16 v[16:31], v[200:203], v[212:215], v[16:31]
	v_mfma_f32_32x32x16_bf16 v[0:15], v[204:207], v[212:215], v[0:15]
	v_mfma_f32_32x32x16_bf16 v[112:127], v[200:203], v[216:219], v[112:127]
	v_mfma_f32_32x32x16_bf16 v[96:111], v[204:207], v[216:219], v[96:111]
	v_mfma_f32_32x32x16_bf16 v[48:63], v[200:203], v[220:223], v[48:63]
	v_mfma_f32_32x32x16_bf16 v[32:47], v[204:207], v[220:223], v[32:47]
	s_waitcnt lgkmcnt(0)
	s_waitcnt vmcnt(0)
	s_barrier
	ds_read_b128 v[200:203], v158 offset:24576
	ds_read_b128 v[204:207], v158 offset:26624
	v_mfma_f32_32x32x16_bf16 v[80:95], v[224:227], v[232:235], v[80:95]
	ds_read_b128 v[208:211], v156 offset:24576
	ds_read_b128 v[212:215], v156 offset:28672
	v_mfma_f32_32x32x16_bf16 v[64:79], v[228:231], v[232:235], v[64:79]
	ds_read_b128 v[216:219], v156 offset:32768
	ds_read_b128 v[220:223], v156 offset:36864
	v_mfma_f32_32x32x16_bf16 v[16:31], v[224:227], v[236:239], v[16:31]
	v_mfma_f32_32x32x16_bf16 v[0:15], v[228:231], v[236:239], v[0:15]
	v_mfma_f32_32x32x16_bf16 v[112:127], v[224:227], v[240:243], v[112:127]
	v_mfma_f32_32x32x16_bf16 v[96:111], v[228:231], v[240:243], v[96:111]
	v_mfma_f32_32x32x16_bf16 v[48:63], v[224:227], v[152:155], v[48:63]
	v_mfma_f32_32x32x16_bf16 v[32:47], v[228:231], v[152:155], v[32:47]
	s_waitcnt lgkmcnt(0)
	ds_read_b128 v[224:227], v159 offset:24576
	ds_read_b128 v[228:231], v159 offset:26624
	v_mfma_f32_32x32x16_bf16 v[80:95], v[200:203], v[208:211], v[80:95]
	ds_read_b128 v[232:235], v157 offset:24576
	ds_read_b128 v[236:239], v157 offset:28672
	v_mfma_f32_32x32x16_bf16 v[64:79], v[204:207], v[208:211], v[64:79]
	ds_read_b128 v[240:243], v157 offset:32768
	ds_read_b128 v[152:155], v157 offset:36864
	v_mfma_f32_32x32x16_bf16 v[16:31], v[200:203], v[212:215], v[16:31]
	v_mfma_f32_32x32x16_bf16 v[0:15], v[204:207], v[212:215], v[0:15]
	v_mfma_f32_32x32x16_bf16 v[112:127], v[200:203], v[216:219], v[112:127]
	v_mfma_f32_32x32x16_bf16 v[96:111], v[204:207], v[216:219], v[96:111]
	v_mfma_f32_32x32x16_bf16 v[48:63], v[200:203], v[220:223], v[48:63]
	v_mfma_f32_32x32x16_bf16 v[32:47], v[204:207], v[220:223], v[32:47]
	s_waitcnt lgkmcnt(0)
	v_mfma_f32_32x32x16_bf16 v[80:95], v[224:227], v[232:235], v[80:95]
	v_mfma_f32_32x32x16_bf16 v[64:79], v[228:231], v[232:235], v[64:79]
	v_mfma_f32_32x32x16_bf16 v[16:31], v[224:227], v[236:239], v[16:31]
	v_mfma_f32_32x32x16_bf16 v[0:15], v[228:231], v[236:239], v[0:15]
	v_mfma_f32_32x32x16_bf16 v[112:127], v[224:227], v[240:243], v[112:127]
	v_mfma_f32_32x32x16_bf16 v[96:111], v[228:231], v[240:243], v[96:111]
	v_mfma_f32_32x32x16_bf16 v[48:63], v[224:227], v[152:155], v[48:63]
	v_mfma_f32_32x32x16_bf16 v[32:47], v[228:231], v[152:155], v[32:47]
	s_nop 15
